# S5 pass2 output epilogue: 16 serial 2-byte input loads issued together before the GELU/store chain; attention VALU trims
# speedup vs baseline: 1.0025x; 1.0025x over previous
.LBB0_1811:
	s_or_b64 exec, exec, s[0:1]
	s_waitcnt vmcnt(0) lgkmcnt(0)
	v_mfma_f32_16x16x32_bf16 v[94:97], v[16:19], v[40:43], 0
	v_mul_u32_u24_e32 v86, 0x210, v93
	v_lshlrev_b32_e32 v87, 2, v92
	v_lshlrev_b32_e32 v86, 2, v86
	v_mfma_f32_16x16x32_bf16 v[98:101], v[16:19], v[36:39], 0
	v_add3_u32 v88, v81, v87, v86
	v_add_u32_e32 v89, 0x400, v88
	v_mul_u32_u24_e32 v103, 0x110, v92
	s_nop 4
	ds_write2_b32 v88, v94, v98 offset1:16
	ds_write2_b32 v88, v95, v99 offset0:132 offset1:148
	ds_write2_b32 v89, v96, v100 offset0:8 offset1:24
	ds_write2_b32 v89, v97, v101 offset0:140 offset1:156
	v_mfma_f32_16x16x32_bf16 v[92:95], v[16:19], v[48:51], 0
	v_lshl_add_u32 v87, v91, 2, v81
	v_add3_u32 v81, v81, v128, v103
	v_pk_add_f32 v[0:1], v[0:1], 0 op_sel_hi:[1,0]
	v_mfma_f32_16x16x32_bf16 v[96:99], v[16:19], v[44:47], 0
	s_nop 7
	ds_write2_b32 v88, v92, v96 offset0:32 offset1:48
	ds_write2_b32 v88, v93, v97 offset0:164 offset1:180
	ds_write2_b32 v89, v94, v98 offset0:40 offset1:56
	ds_write2_b32 v89, v95, v99 offset0:172 offset1:188
	v_mfma_f32_16x16x32_bf16 v[92:95], v[16:19], v[56:59], 0
	v_readlane_b32 s68, v251, 41
	v_readlane_b32 s76, v251, 49
	v_readlane_b32 s77, v251, 50
	v_mfma_f32_16x16x32_bf16 v[96:99], v[16:19], v[52:55], 0
	s_nop 7
	ds_write2_b32 v88, v92, v96 offset0:64 offset1:80
	ds_write2_b32 v88, v93, v97 offset0:196 offset1:212
	ds_write2_b32 v89, v94, v98 offset0:72 offset1:88
	ds_write2_b32 v89, v95, v99 offset0:204 offset1:220
	v_mfma_f32_16x16x32_bf16 v[92:95], v[16:19], v[64:67], 0
	s_mov_b32 s10, 0x3f200000
	v_readlane_b32 s69, v251, 42
	v_readlane_b32 s70, v251, 43
	v_mfma_f32_16x16x32_bf16 v[16:19], v[16:19], v[60:63], 0
	s_nop 7
	ds_write2_b32 v88, v92, v16 offset0:96 offset1:112
	ds_write2_b32 v88, v93, v17 offset0:228 offset1:244
	ds_write2_b32 v89, v94, v18 offset0:104 offset1:120
	ds_write2_b32 v89, v95, v19 offset0:236 offset1:252
	v_lshlrev_b32_e32 v16, 1, v91
	v_add_u32_e32 v91, 0xf0, v87
	s_waitcnt vmcnt(0) lgkmcnt(0)
	v_sub_u32_e32 v86, v87, v16
	ds_read2st64_b32 v[16:17], v91 offset0:30 offset1:31
	v_mul_f32_e32 v18, v85, v83
	v_fma_f32 v18, v84, v82, -v18
	v_mfma_f32_16x16x32_bf16 v[108:111], v[72:75], v[36:39], 0
	v_readlane_b32 s71, v251, 44
	s_waitcnt lgkmcnt(0)
	v_add_f32_e32 v18, v18, v16
	v_mul_f32_e32 v16, v84, v83
	v_fmac_f32_e32 v16, v85, v82
	v_add_f32_e32 v19, v16, v17
	v_cvt_pk_bf16_f32 v16, v18, s0
	ds_write_b16 v86, v16 offset:12528
	v_cvt_pk_bf16_f32 v16, v19, s0
	v_add_u32_e32 v84, 0xe0, v87
	ds_write_b16 v86, v16 offset:12656
	ds_read2st64_b32 v[16:17], v84 offset0:28 offset1:29
	v_mul_f32_e32 v85, v83, v19
	v_fma_f32 v85, v82, v18, -v85
	v_readlane_b32 s72, v251, 45
	v_readlane_b32 s73, v251, 46
	s_waitcnt lgkmcnt(0)
	v_add_f32_e32 v92, v16, v85
	v_mul_f32_e32 v16, v82, v19
	v_fmac_f32_e32 v16, v83, v18
	v_add_f32_e32 v18, v16, v17
	v_cvt_pk_bf16_f32 v16, v92, s0
	ds_write_b16 v86, v16 offset:12256
	v_cvt_pk_bf16_f32 v16, v18, s0
	v_add_u32_e32 v85, 0xd0, v87
	ds_write_b16 v86, v16 offset:12384
	ds_read2st64_b32 v[16:17], v85 offset0:26 offset1:27
	v_mul_f32_e32 v19, v83, v18
	v_fma_f32 v19, v82, v92, -v19
	v_readlane_b32 s74, v251, 47
	v_readlane_b32 s75, v251, 48
	s_waitcnt lgkmcnt(0)
	v_add_f32_e32 v19, v16, v19
	v_mul_f32_e32 v16, v82, v18
	v_fmac_f32_e32 v16, v83, v92
	v_add_f32_e32 v18, v16, v17
	v_cvt_pk_bf16_f32 v16, v19, s0
	ds_write_b16 v86, v16 offset:11984
	v_cvt_pk_bf16_f32 v16, v18, s0
	v_add_u32_e32 v92, 0xc0, v87
	ds_write_b16 v86, v16 offset:12112
	ds_read2st64_b32 v[16:17], v92 offset0:24 offset1:25
	v_mul_f32_e32 v93, v83, v18
	v_fma_f32 v93, v82, v19, -v93
	v_readlane_b32 s78, v251, 51
	v_readlane_b32 s79, v251, 52
	s_waitcnt lgkmcnt(0)
	v_add_f32_e32 v94, v16, v93
	v_mul_f32_e32 v16, v82, v18
	v_fmac_f32_e32 v16, v83, v19
	v_add_f32_e32 v18, v16, v17
	v_cvt_pk_bf16_f32 v16, v94, s0
	ds_write_b16 v86, v16 offset:11712
	v_cvt_pk_bf16_f32 v16, v18, s0
	v_add_u32_e32 v93, 0xb0, v87
	ds_write_b16 v86, v16 offset:11840
	ds_read2st64_b32 v[16:17], v93 offset0:22 offset1:23
	v_mul_f32_e32 v19, v83, v18
	v_fma_f32 v19, v82, v94, -v19
	v_readlane_b32 s80, v251, 53
	v_readlane_b32 s81, v251, 54
	s_waitcnt lgkmcnt(0)
	v_add_f32_e32 v19, v16, v19
	v_mul_f32_e32 v16, v82, v18
	v_fmac_f32_e32 v16, v83, v94
	v_add_f32_e32 v18, v16, v17
	v_cvt_pk_bf16_f32 v16, v19, s0
	ds_write_b16 v86, v16 offset:11440
	v_cvt_pk_bf16_f32 v16, v18, s0
	v_add_u32_e32 v94, 0xa0, v87
	ds_write_b16 v86, v16 offset:11568
	ds_read2st64_b32 v[16:17], v94 offset0:20 offset1:21
	v_mul_f32_e32 v95, v83, v18
	v_fma_f32 v95, v82, v19, -v95
	v_readlane_b32 s82, v251, 55
	v_readlane_b32 s83, v251, 56
	s_waitcnt lgkmcnt(0)
	v_add_f32_e32 v96, v16, v95
	v_mul_f32_e32 v16, v82, v18
	v_fmac_f32_e32 v16, v83, v19
	v_add_f32_e32 v18, v16, v17
	v_cvt_pk_bf16_f32 v16, v96, s0
	ds_write_b16 v86, v16 offset:11168
	v_cvt_pk_bf16_f32 v16, v18, s0
	v_add_u32_e32 v95, 0x90, v87
	ds_write_b16 v86, v16 offset:11296
	ds_read2st64_b32 v[16:17], v95 offset0:18 offset1:19
	v_mul_f32_e32 v19, v83, v18
	v_fma_f32 v19, v82, v96, -v19
	s_waitcnt lgkmcnt(0)
	v_add_f32_e32 v19, v16, v19
	v_mul_f32_e32 v16, v82, v18
	v_fmac_f32_e32 v16, v83, v96
	v_add_f32_e32 v18, v16, v17
	v_cvt_pk_bf16_f32 v16, v19, s0
	ds_write_b16 v86, v16 offset:10896
	v_cvt_pk_bf16_f32 v16, v18, s0
	v_add_u32_e32 v96, 0x80, v87
	ds_write_b16 v86, v16 offset:11024
	ds_read2st64_b32 v[16:17], v96 offset0:16 offset1:17
	v_mul_f32_e32 v97, v83, v18
	v_fma_f32 v97, v82, v19, -v97
	s_waitcnt lgkmcnt(0)
	v_add_f32_e32 v98, v16, v97
	v_mul_f32_e32 v16, v82, v18
	v_fmac_f32_e32 v16, v83, v19
	v_add_f32_e32 v18, v16, v17
	v_cvt_pk_bf16_f32 v16, v98, s0
	ds_write_b16 v86, v16 offset:10624
	v_cvt_pk_bf16_f32 v16, v18, s0
	v_add_u32_e32 v97, 0x70, v87
	ds_write_b16 v86, v16 offset:10752
	ds_read2st64_b32 v[16:17], v97 offset0:14 offset1:15
	v_mul_f32_e32 v19, v83, v18
	v_fma_f32 v19, v82, v98, -v19
	s_waitcnt lgkmcnt(0)
	v_add_f32_e32 v19, v16, v19
	v_mul_f32_e32 v16, v82, v18
	v_fmac_f32_e32 v16, v83, v98
	v_add_f32_e32 v18, v16, v17
	v_cvt_pk_bf16_f32 v16, v19, s0
	ds_write_b16 v86, v16 offset:10352
	v_cvt_pk_bf16_f32 v16, v18, s0
	v_add_u32_e32 v98, 0x60, v87
	ds_write_b16 v86, v16 offset:10480
	ds_read2st64_b32 v[16:17], v98 offset0:12 offset1:13
	v_mul_f32_e32 v99, v83, v18
	v_fma_f32 v99, v82, v19, -v99
	s_waitcnt lgkmcnt(0)
	v_add_f32_e32 v100, v16, v99
	v_mul_f32_e32 v16, v82, v18
	v_fmac_f32_e32 v16, v83, v19
	v_add_f32_e32 v18, v16, v17
	v_cvt_pk_bf16_f32 v16, v100, s0
	ds_write_b16 v86, v16 offset:10080
	v_cvt_pk_bf16_f32 v16, v18, s0
	v_add_u32_e32 v99, 0x50, v87
	ds_write_b16 v86, v16 offset:10208
	ds_read2st64_b32 v[16:17], v99 offset0:10 offset1:11
	v_mul_f32_e32 v19, v83, v18
	v_fma_f32 v19, v82, v100, -v19
	s_waitcnt lgkmcnt(0)
	v_add_f32_e32 v19, v16, v19
	v_mul_f32_e32 v16, v82, v18
	v_fmac_f32_e32 v16, v83, v100
	v_add_f32_e32 v18, v16, v17
	v_cvt_pk_bf16_f32 v16, v19, s0
	ds_write_b16 v86, v16 offset:9808
	v_cvt_pk_bf16_f32 v16, v18, s0
	v_add_u32_e32 v100, 64, v87
	ds_write_b16 v86, v16 offset:9936
	ds_read2st64_b32 v[16:17], v100 offset0:8 offset1:9
	v_mul_f32_e32 v101, v83, v18
	v_fma_f32 v101, v82, v19, -v101
	s_waitcnt lgkmcnt(0)
	v_add_f32_e32 v102, v16, v101
	v_mul_f32_e32 v16, v82, v18
	v_fmac_f32_e32 v16, v83, v19
	v_add_f32_e32 v18, v16, v17
	v_cvt_pk_bf16_f32 v16, v102, s0
	ds_write_b16 v86, v16 offset:9536
	v_cvt_pk_bf16_f32 v16, v18, s0
	v_add_u32_e32 v101, 48, v87
	ds_write_b16 v86, v16 offset:9664
	ds_read2st64_b32 v[16:17], v101 offset0:6 offset1:7
	v_mul_f32_e32 v19, v83, v18
	v_fma_f32 v19, v82, v102, -v19
	s_waitcnt lgkmcnt(0)
	v_add_f32_e32 v19, v16, v19
	v_mul_f32_e32 v16, v82, v18
	v_fmac_f32_e32 v16, v83, v102
	v_add_f32_e32 v18, v16, v17
	v_cvt_pk_bf16_f32 v16, v19, s0
	ds_write_b16 v86, v16 offset:9264
	v_cvt_pk_bf16_f32 v16, v18, s0
	v_add_u32_e32 v102, 32, v87
	ds_write_b16 v86, v16 offset:9392
	ds_read2st64_b32 v[16:17], v102 offset0:4 offset1:5
	v_mul_f32_e32 v104, v83, v18
	v_fma_f32 v104, v82, v19, -v104
	s_waitcnt lgkmcnt(0)
	v_add_f32_e32 v104, v16, v104
	v_mul_f32_e32 v16, v82, v18
	v_fmac_f32_e32 v16, v83, v19
	v_add_f32_e32 v18, v16, v17
	v_cvt_pk_bf16_f32 v16, v104, s0
	ds_write_b16 v86, v16 offset:8992
	v_cvt_pk_bf16_f32 v16, v18, s0
	ds_write_b16 v86, v16 offset:9120
	ds_read2_b32 v[16:17], v87 offset0:132 offset1:196
	v_mul_f32_e32 v19, v83, v18
	v_fma_f32 v19, v82, v104, -v19
	s_waitcnt lgkmcnt(0)
	v_add_f32_e32 v19, v16, v19
	v_mul_f32_e32 v16, v82, v18
	v_fmac_f32_e32 v16, v83, v104
	v_add_f32_e32 v18, v16, v17
	v_cvt_pk_bf16_f32 v16, v19, s0
	ds_write_b16 v86, v16 offset:8720
	v_cvt_pk_bf16_f32 v16, v18, s0
	ds_write_b16 v86, v16 offset:8848
	ds_read2st64_b32 v[16:17], v87 offset1:1
	v_mul_f32_e32 v104, v83, v18
	v_fma_f32 v104, v82, v19, -v104
	s_waitcnt lgkmcnt(0)
	v_add_f32_e32 v112, v16, v104
	v_mul_f32_e32 v16, v82, v18
	v_fmac_f32_e32 v16, v83, v19
	v_add_f32_e32 v113, v16, v17
	v_cvt_pk_bf16_f32 v16, v112, s0
	ds_write_b16 v86, v16 offset:8448
	v_cvt_pk_bf16_f32 v16, v113, s0
	ds_write_b16 v86, v16 offset:8576
	s_waitcnt vmcnt(0) lgkmcnt(0)
	ds_read_b128 v[16:19], v81 offset:8448
	ds_read_b128 v[104:107], v81 offset:8512
	s_waitcnt lgkmcnt(1)
	v_mfma_f32_16x16x32_bf16 v[16:19], v[16:19], v[32:35], 0
	s_waitcnt lgkmcnt(0)
	v_mfma_f32_16x16x32_bf16 v[16:19], v[104:107], v[28:31], v[16:19]
	ds_read_b128 v[104:107], v81 offset:8576
	s_waitcnt lgkmcnt(0)
	v_mfma_f32_16x16x32_bf16 v[16:19], v[104:107], v[24:27], v[16:19]
	ds_read_b128 v[104:107], v81 offset:8640
	s_waitcnt lgkmcnt(0)
	v_mfma_f32_16x16x32_bf16 v[16:19], v[104:107], v[20:23], v[16:19]
	v_mfma_f32_16x16x32_bf16 v[104:107], v[72:75], v[40:43], 0
	s_nop 7
	ds_write2_b32 v88, v104, v108 offset1:16
	ds_write2_b32 v88, v105, v109 offset0:132 offset1:148
	ds_write2_b32 v89, v106, v110 offset0:8 offset1:24
	ds_write2_b32 v89, v107, v111 offset0:140 offset1:156
	v_mfma_f32_16x16x32_bf16 v[104:107], v[72:75], v[48:51], 0
	v_mfma_f32_16x16x32_bf16 v[108:111], v[72:75], v[44:47], 0
	s_nop 7
	ds_write2_b32 v88, v104, v108 offset0:32 offset1:48
	ds_write2_b32 v88, v105, v109 offset0:164 offset1:180
	ds_write2_b32 v89, v106, v110 offset0:40 offset1:56
	ds_write2_b32 v89, v107, v111 offset0:172 offset1:188
	v_mfma_f32_16x16x32_bf16 v[104:107], v[72:75], v[56:59], 0
	v_mfma_f32_16x16x32_bf16 v[108:111], v[72:75], v[52:55], 0
	s_nop 7
	ds_write2_b32 v88, v104, v108 offset0:64 offset1:80
	ds_write2_b32 v88, v105, v109 offset0:196 offset1:212
	ds_write2_b32 v89, v106, v110 offset0:72 offset1:88
	ds_write2_b32 v89, v107, v111 offset0:204 offset1:220
	v_mfma_f32_16x16x32_bf16 v[104:107], v[72:75], v[64:67], 0
	v_mfma_f32_16x16x32_bf16 v[72:75], v[72:75], v[60:63], 0
	s_nop 7
	ds_write2_b32 v88, v104, v72 offset0:96 offset1:112
	ds_write2_b32 v88, v105, v73 offset0:228 offset1:244
	ds_write2_b32 v89, v106, v74 offset0:104 offset1:120
	ds_write2_b32 v89, v107, v75 offset0:236 offset1:252
	s_waitcnt vmcnt(0) lgkmcnt(0)
	ds_read2st64_b32 v[72:73], v91 offset0:30 offset1:31
	v_mul_f32_e32 v74, v83, v113
	v_fma_f32 v74, v82, v112, -v74
	v_mfma_f32_16x16x32_bf16 v[108:111], v[76:79], v[36:39], 0
	s_waitcnt lgkmcnt(0)
	v_add_f32_e32 v74, v74, v72
	v_mul_f32_e32 v72, v82, v113
	v_fmac_f32_e32 v72, v83, v112
	v_add_f32_e32 v75, v72, v73
	v_cvt_pk_bf16_f32 v72, v74, s0
	ds_write_b16 v86, v72 offset:12528
	v_cvt_pk_bf16_f32 v72, v75, s0
	ds_write_b16 v86, v72 offset:12656
	ds_read2st64_b32 v[72:73], v84 offset0:28 offset1:29
	v_mul_f32_e32 v103, v83, v75
	v_fma_f32 v103, v82, v74, -v103
	v_mfma_f32_16x16x32_bf16 v[36:39], v[68:71], v[36:39], 0
	s_waitcnt lgkmcnt(0)
	v_add_f32_e32 v103, v72, v103
	v_mul_f32_e32 v72, v82, v75
	v_fmac_f32_e32 v72, v83, v74
	v_add_f32_e32 v74, v72, v73
	v_cvt_pk_bf16_f32 v72, v103, s0
	ds_write_b16 v86, v72 offset:12256
	v_cvt_pk_bf16_f32 v72, v74, s0
	ds_write_b16 v86, v72 offset:12384
	ds_read2st64_b32 v[72:73], v85 offset0:26 offset1:27
	v_mul_f32_e32 v75, v83, v74
	v_fma_f32 v75, v82, v103, -v75
	s_waitcnt lgkmcnt(0)
	v_add_f32_e32 v75, v72, v75
	v_mul_f32_e32 v72, v82, v74
	v_fmac_f32_e32 v72, v83, v103
	v_add_f32_e32 v74, v72, v73
	v_cvt_pk_bf16_f32 v72, v75, s0
	ds_write_b16 v86, v72 offset:11984
	v_cvt_pk_bf16_f32 v72, v74, s0
	ds_write_b16 v86, v72 offset:12112
	ds_read2st64_b32 v[72:73], v92 offset0:24 offset1:25
	v_mul_f32_e32 v103, v83, v74
	v_fma_f32 v103, v82, v75, -v103
	s_waitcnt lgkmcnt(0)
	v_add_f32_e32 v103, v72, v103
	v_mul_f32_e32 v72, v82, v74
	v_fmac_f32_e32 v72, v83, v75
	v_add_f32_e32 v74, v72, v73
	v_cvt_pk_bf16_f32 v72, v103, s0
	ds_write_b16 v86, v72 offset:11712
	v_cvt_pk_bf16_f32 v72, v74, s0
	ds_write_b16 v86, v72 offset:11840
	ds_read2st64_b32 v[72:73], v93 offset0:22 offset1:23
	v_mul_f32_e32 v75, v83, v74
	v_fma_f32 v75, v82, v103, -v75
	s_waitcnt lgkmcnt(0)
	v_add_f32_e32 v75, v72, v75
	v_mul_f32_e32 v72, v82, v74
	v_fmac_f32_e32 v72, v83, v103
	v_add_f32_e32 v74, v72, v73
	v_cvt_pk_bf16_f32 v72, v75, s0
	ds_write_b16 v86, v72 offset:11440
	v_cvt_pk_bf16_f32 v72, v74, s0
	ds_write_b16 v86, v72 offset:11568
	ds_read2st64_b32 v[72:73], v94 offset0:20 offset1:21
	v_mul_f32_e32 v103, v83, v74
	v_fma_f32 v103, v82, v75, -v103
	s_waitcnt lgkmcnt(0)
	v_add_f32_e32 v103, v72, v103
	v_mul_f32_e32 v72, v82, v74
	v_fmac_f32_e32 v72, v83, v75
	v_add_f32_e32 v74, v72, v73
	v_cvt_pk_bf16_f32 v72, v103, s0
	ds_write_b16 v86, v72 offset:11168
	v_cvt_pk_bf16_f32 v72, v74, s0
	ds_write_b16 v86, v72 offset:11296
	ds_read2st64_b32 v[72:73], v95 offset0:18 offset1:19
	v_mul_f32_e32 v75, v83, v74
	v_fma_f32 v75, v82, v103, -v75
	s_waitcnt lgkmcnt(0)
	v_add_f32_e32 v75, v72, v75
	v_mul_f32_e32 v72, v82, v74
	v_fmac_f32_e32 v72, v83, v103
	v_add_f32_e32 v74, v72, v73
	v_cvt_pk_bf16_f32 v72, v75, s0
	ds_write_b16 v86, v72 offset:10896
	v_cvt_pk_bf16_f32 v72, v74, s0
	ds_write_b16 v86, v72 offset:11024
	ds_read2st64_b32 v[72:73], v96 offset0:16 offset1:17
	v_mul_f32_e32 v103, v83, v74
	v_fma_f32 v103, v82, v75, -v103
	s_waitcnt lgkmcnt(0)
	v_add_f32_e32 v103, v72, v103
	v_mul_f32_e32 v72, v82, v74
	v_fmac_f32_e32 v72, v83, v75
	v_add_f32_e32 v74, v72, v73
	v_cvt_pk_bf16_f32 v72, v103, s0
	ds_write_b16 v86, v72 offset:10624
	v_cvt_pk_bf16_f32 v72, v74, s0
	ds_write_b16 v86, v72 offset:10752
	ds_read2st64_b32 v[72:73], v97 offset0:14 offset1:15
	v_mul_f32_e32 v75, v83, v74
	v_fma_f32 v75, v82, v103, -v75
	s_waitcnt lgkmcnt(0)
	v_add_f32_e32 v75, v72, v75
	v_mul_f32_e32 v72, v82, v74
	v_fmac_f32_e32 v72, v83, v103
	v_add_f32_e32 v74, v72, v73
	v_cvt_pk_bf16_f32 v72, v75, s0
	ds_write_b16 v86, v72 offset:10352
	v_cvt_pk_bf16_f32 v72, v74, s0
	ds_write_b16 v86, v72 offset:10480
	ds_read2st64_b32 v[72:73], v98 offset0:12 offset1:13
	v_mul_f32_e32 v103, v83, v74
	v_fma_f32 v103, v82, v75, -v103
	s_waitcnt lgkmcnt(0)
	v_add_f32_e32 v103, v72, v103
	v_mul_f32_e32 v72, v82, v74
	v_fmac_f32_e32 v72, v83, v75
	v_add_f32_e32 v74, v72, v73
	v_cvt_pk_bf16_f32 v72, v103, s0
	ds_write_b16 v86, v72 offset:10080
	v_cvt_pk_bf16_f32 v72, v74, s0
	ds_write_b16 v86, v72 offset:10208
	ds_read2st64_b32 v[72:73], v99 offset0:10 offset1:11
	v_mul_f32_e32 v75, v83, v74
	v_fma_f32 v75, v82, v103, -v75
	s_waitcnt lgkmcnt(0)
	v_add_f32_e32 v75, v72, v75
	v_mul_f32_e32 v72, v82, v74
	v_fmac_f32_e32 v72, v83, v103
	v_add_f32_e32 v74, v72, v73
	v_cvt_pk_bf16_f32 v72, v75, s0
	ds_write_b16 v86, v72 offset:9808
	v_cvt_pk_bf16_f32 v72, v74, s0
	ds_write_b16 v86, v72 offset:9936
	ds_read2st64_b32 v[72:73], v100 offset0:8 offset1:9
	v_mul_f32_e32 v103, v83, v74
	v_fma_f32 v103, v82, v75, -v103
	s_waitcnt lgkmcnt(0)
	v_add_f32_e32 v103, v72, v103
	v_mul_f32_e32 v72, v82, v74
	v_fmac_f32_e32 v72, v83, v75
	v_add_f32_e32 v74, v72, v73
	v_cvt_pk_bf16_f32 v72, v103, s0
	ds_write_b16 v86, v72 offset:9536
	v_cvt_pk_bf16_f32 v72, v74, s0
	ds_write_b16 v86, v72 offset:9664
	ds_read2st64_b32 v[72:73], v101 offset0:6 offset1:7
	v_mul_f32_e32 v75, v83, v74
	v_fma_f32 v75, v82, v103, -v75
	s_waitcnt lgkmcnt(0)
	v_add_f32_e32 v75, v72, v75
	v_mul_f32_e32 v72, v82, v74
	v_fmac_f32_e32 v72, v83, v103
	v_add_f32_e32 v74, v72, v73
	v_cvt_pk_bf16_f32 v72, v75, s0
	ds_write_b16 v86, v72 offset:9264
	v_cvt_pk_bf16_f32 v72, v74, s0
	ds_write_b16 v86, v72 offset:9392
	ds_read2st64_b32 v[72:73], v102 offset0:4 offset1:5
	v_mul_f32_e32 v103, v83, v74
	v_fma_f32 v103, v82, v75, -v103
	s_waitcnt lgkmcnt(0)
	v_add_f32_e32 v103, v72, v103
	v_mul_f32_e32 v72, v82, v74
	v_fmac_f32_e32 v72, v83, v75
	v_add_f32_e32 v74, v72, v73
	v_cvt_pk_bf16_f32 v72, v103, s0
	ds_write_b16 v86, v72 offset:8992
	v_cvt_pk_bf16_f32 v72, v74, s0
	ds_write_b16 v86, v72 offset:9120
	ds_read2_b32 v[72:73], v87 offset0:132 offset1:196
	v_mul_f32_e32 v75, v83, v74
	v_fma_f32 v75, v82, v103, -v75
	s_waitcnt lgkmcnt(0)
	v_add_f32_e32 v75, v72, v75
	v_mul_f32_e32 v72, v82, v74
	v_fmac_f32_e32 v72, v83, v103
	v_add_f32_e32 v74, v72, v73
	v_cvt_pk_bf16_f32 v72, v75, s0
	ds_write_b16 v86, v72 offset:8720
	v_cvt_pk_bf16_f32 v72, v74, s0
	ds_write_b16 v86, v72 offset:8848
	ds_read2st64_b32 v[72:73], v87 offset1:1
	v_mul_f32_e32 v103, v83, v74
	v_fma_f32 v103, v82, v75, -v103
	s_waitcnt lgkmcnt(0)
	v_add_f32_e32 v103, v72, v103
	v_mul_f32_e32 v72, v82, v74
	v_fmac_f32_e32 v72, v83, v75
	v_add_f32_e32 v112, v72, v73
	v_cvt_pk_bf16_f32 v72, v103, s0
	ds_write_b16 v86, v72 offset:8448
	v_cvt_pk_bf16_f32 v72, v112, s0
	ds_write_b16 v86, v72 offset:8576
	s_waitcnt vmcnt(0) lgkmcnt(0)
	ds_read_b128 v[72:75], v81 offset:8448
	ds_read_b128 v[104:107], v81 offset:8512
	s_waitcnt lgkmcnt(1)
	v_mfma_f32_16x16x32_bf16 v[72:75], v[72:75], v[32:35], 0
	s_waitcnt lgkmcnt(0)
	v_mfma_f32_16x16x32_bf16 v[72:75], v[104:107], v[28:31], v[72:75]
	ds_read_b128 v[104:107], v81 offset:8576
	s_waitcnt lgkmcnt(0)
	v_mfma_f32_16x16x32_bf16 v[72:75], v[104:107], v[24:27], v[72:75]
	ds_read_b128 v[104:107], v81 offset:8640
	s_waitcnt lgkmcnt(0)
	v_mfma_f32_16x16x32_bf16 v[72:75], v[104:107], v[20:23], v[72:75]
	v_mfma_f32_16x16x32_bf16 v[104:107], v[76:79], v[40:43], 0
	s_nop 7
	ds_write2_b32 v88, v104, v108 offset1:16
	ds_write2_b32 v88, v105, v109 offset0:132 offset1:148
	ds_write2_b32 v89, v106, v110 offset0:8 offset1:24
	ds_write2_b32 v89, v107, v111 offset0:140 offset1:156
	v_mfma_f32_16x16x32_bf16 v[104:107], v[76:79], v[48:51], 0
	v_mfma_f32_16x16x32_bf16 v[108:111], v[76:79], v[44:47], 0
	s_nop 7
	ds_write2_b32 v88, v104, v108 offset0:32 offset1:48
	ds_write2_b32 v88, v105, v109 offset0:164 offset1:180
	ds_write2_b32 v89, v106, v110 offset0:40 offset1:56
	ds_write2_b32 v89, v107, v111 offset0:172 offset1:188
	v_mfma_f32_16x16x32_bf16 v[104:107], v[76:79], v[56:59], 0
	v_mfma_f32_16x16x32_bf16 v[108:111], v[76:79], v[52:55], 0
	s_nop 7
	ds_write2_b32 v88, v104, v108 offset0:64 offset1:80
	ds_write2_b32 v88, v105, v109 offset0:196 offset1:212
	ds_write2_b32 v89, v106, v110 offset0:72 offset1:88
	ds_write2_b32 v89, v107, v111 offset0:204 offset1:220
	v_mfma_f32_16x16x32_bf16 v[104:107], v[76:79], v[64:67], 0
	v_mfma_f32_16x16x32_bf16 v[76:79], v[76:79], v[60:63], 0
	s_nop 7
	ds_write2_b32 v88, v104, v76 offset0:96 offset1:112
	ds_write2_b32 v88, v105, v77 offset0:228 offset1:244
	ds_write2_b32 v89, v106, v78 offset0:104 offset1:120
	ds_write2_b32 v89, v107, v79 offset0:236 offset1:252
	s_waitcnt vmcnt(0) lgkmcnt(0)
	ds_read2st64_b32 v[76:77], v91 offset0:30 offset1:31
	v_mul_f32_e32 v78, v83, v112
	v_fma_f32 v78, v82, v103, -v78
	v_mfma_f32_16x16x32_bf16 v[40:43], v[68:71], v[40:43], 0
	s_waitcnt lgkmcnt(0)
	v_add_f32_e32 v78, v78, v76
	v_mul_f32_e32 v76, v82, v112
	v_fmac_f32_e32 v76, v83, v103
	v_add_f32_e32 v79, v76, v77
	v_cvt_pk_bf16_f32 v76, v78, s0
	ds_write_b16 v86, v76 offset:12528
	v_cvt_pk_bf16_f32 v76, v79, s0
	ds_write_b16 v86, v76 offset:12656
	ds_read2st64_b32 v[76:77], v84 offset0:28 offset1:29
	v_mul_f32_e32 v103, v83, v79
	v_fma_f32 v103, v82, v78, -v103
	s_waitcnt lgkmcnt(0)
	v_add_f32_e32 v103, v76, v103
	v_mul_f32_e32 v76, v82, v79
	v_fmac_f32_e32 v76, v83, v78
	v_add_f32_e32 v78, v76, v77
	v_cvt_pk_bf16_f32 v76, v103, s0
	ds_write_b16 v86, v76 offset:12256
	v_cvt_pk_bf16_f32 v76, v78, s0
	ds_write_b16 v86, v76 offset:12384
	ds_read2st64_b32 v[76:77], v85 offset0:26 offset1:27
	v_mul_f32_e32 v79, v83, v78
	v_fma_f32 v79, v82, v103, -v79
	s_waitcnt lgkmcnt(0)
	v_add_f32_e32 v79, v76, v79
	v_mul_f32_e32 v76, v82, v78
	v_fmac_f32_e32 v76, v83, v103
	v_add_f32_e32 v78, v76, v77
	v_cvt_pk_bf16_f32 v76, v79, s0
	ds_write_b16 v86, v76 offset:11984
	v_cvt_pk_bf16_f32 v76, v78, s0
	ds_write_b16 v86, v76 offset:12112
	ds_read2st64_b32 v[76:77], v92 offset0:24 offset1:25
	v_mul_f32_e32 v103, v83, v78
	v_fma_f32 v103, v82, v79, -v103
	s_waitcnt lgkmcnt(0)
	v_add_f32_e32 v103, v76, v103
	v_mul_f32_e32 v76, v82, v78
	v_fmac_f32_e32 v76, v83, v79
	v_add_f32_e32 v78, v76, v77
	v_cvt_pk_bf16_f32 v76, v103, s0
	ds_write_b16 v86, v76 offset:11712
	v_cvt_pk_bf16_f32 v76, v78, s0
	ds_write_b16 v86, v76 offset:11840
	ds_read2st64_b32 v[76:77], v93 offset0:22 offset1:23
	v_mul_f32_e32 v79, v83, v78
	v_fma_f32 v79, v82, v103, -v79
	s_waitcnt lgkmcnt(0)
	v_add_f32_e32 v79, v76, v79
	v_mul_f32_e32 v76, v82, v78
	v_fmac_f32_e32 v76, v83, v103
	v_add_f32_e32 v78, v76, v77
	v_cvt_pk_bf16_f32 v76, v79, s0
	ds_write_b16 v86, v76 offset:11440
	v_cvt_pk_bf16_f32 v76, v78, s0
	ds_write_b16 v86, v76 offset:11568
	ds_read2st64_b32 v[76:77], v94 offset0:20 offset1:21
	v_mul_f32_e32 v103, v83, v78
	v_fma_f32 v103, v82, v79, -v103
	s_waitcnt lgkmcnt(0)
	v_add_f32_e32 v103, v76, v103
	v_mul_f32_e32 v76, v82, v78
	v_fmac_f32_e32 v76, v83, v79
	v_add_f32_e32 v78, v76, v77
	v_cvt_pk_bf16_f32 v76, v103, s0
	ds_write_b16 v86, v76 offset:11168
	v_cvt_pk_bf16_f32 v76, v78, s0
	ds_write_b16 v86, v76 offset:11296
	ds_read2st64_b32 v[76:77], v95 offset0:18 offset1:19
	v_mul_f32_e32 v79, v83, v78
	v_fma_f32 v79, v82, v103, -v79
	s_waitcnt lgkmcnt(0)
	v_add_f32_e32 v79, v76, v79
	v_mul_f32_e32 v76, v82, v78
	v_fmac_f32_e32 v76, v83, v103
	v_add_f32_e32 v78, v76, v77
	v_cvt_pk_bf16_f32 v76, v79, s0
	ds_write_b16 v86, v76 offset:10896
	v_cvt_pk_bf16_f32 v76, v78, s0
	ds_write_b16 v86, v76 offset:11024
	ds_read2st64_b32 v[76:77], v96 offset0:16 offset1:17
	v_mul_f32_e32 v103, v83, v78
	v_fma_f32 v103, v82, v79, -v103
	s_waitcnt lgkmcnt(0)
	v_add_f32_e32 v103, v76, v103
	v_mul_f32_e32 v76, v82, v78
	v_fmac_f32_e32 v76, v83, v79
	v_add_f32_e32 v78, v76, v77
	v_cvt_pk_bf16_f32 v76, v103, s0
	ds_write_b16 v86, v76 offset:10624
	v_cvt_pk_bf16_f32 v76, v78, s0
	ds_write_b16 v86, v76 offset:10752
	ds_read2st64_b32 v[76:77], v97 offset0:14 offset1:15
	v_mul_f32_e32 v79, v83, v78
	v_fma_f32 v79, v82, v103, -v79
	s_waitcnt lgkmcnt(0)
	v_add_f32_e32 v79, v76, v79
	v_mul_f32_e32 v76, v82, v78
	v_fmac_f32_e32 v76, v83, v103
	v_add_f32_e32 v78, v76, v77
	v_cvt_pk_bf16_f32 v76, v79, s0
	ds_write_b16 v86, v76 offset:10352
	v_cvt_pk_bf16_f32 v76, v78, s0
	ds_write_b16 v86, v76 offset:10480
	ds_read2st64_b32 v[76:77], v98 offset0:12 offset1:13
	v_mul_f32_e32 v103, v83, v78
	v_fma_f32 v103, v82, v79, -v103
	s_waitcnt lgkmcnt(0)
	v_add_f32_e32 v103, v76, v103
	v_mul_f32_e32 v76, v82, v78
	v_fmac_f32_e32 v76, v83, v79
	v_add_f32_e32 v78, v76, v77
	v_cvt_pk_bf16_f32 v76, v103, s0
	ds_write_b16 v86, v76 offset:10080
	v_cvt_pk_bf16_f32 v76, v78, s0
	ds_write_b16 v86, v76 offset:10208
	ds_read2st64_b32 v[76:77], v99 offset0:10 offset1:11
	v_mul_f32_e32 v79, v83, v78
	v_fma_f32 v79, v82, v103, -v79
	s_waitcnt lgkmcnt(0)
	v_add_f32_e32 v79, v76, v79
	v_mul_f32_e32 v76, v82, v78
	v_fmac_f32_e32 v76, v83, v103
	v_add_f32_e32 v78, v76, v77
	v_cvt_pk_bf16_f32 v76, v79, s0
	ds_write_b16 v86, v76 offset:9808
	v_cvt_pk_bf16_f32 v76, v78, s0
	ds_write_b16 v86, v76 offset:9936
	ds_read2st64_b32 v[76:77], v100 offset0:8 offset1:9
	v_mul_f32_e32 v103, v83, v78
	v_fma_f32 v103, v82, v79, -v103
	s_waitcnt lgkmcnt(0)
	v_add_f32_e32 v103, v76, v103
	v_mul_f32_e32 v76, v82, v78
	v_fmac_f32_e32 v76, v83, v79
	v_add_f32_e32 v78, v76, v77
	v_cvt_pk_bf16_f32 v76, v103, s0
	ds_write_b16 v86, v76 offset:9536
	v_cvt_pk_bf16_f32 v76, v78, s0
	ds_write_b16 v86, v76 offset:9664
	ds_read2st64_b32 v[76:77], v101 offset0:6 offset1:7
	v_mul_f32_e32 v79, v83, v78
	v_fma_f32 v79, v82, v103, -v79
	s_waitcnt lgkmcnt(0)
	v_add_f32_e32 v79, v76, v79
	v_mul_f32_e32 v76, v82, v78
	v_fmac_f32_e32 v76, v83, v103
	v_add_f32_e32 v78, v76, v77
	v_cvt_pk_bf16_f32 v76, v79, s0
	ds_write_b16 v86, v76 offset:9264
	v_cvt_pk_bf16_f32 v76, v78, s0
	ds_write_b16 v86, v76 offset:9392
	ds_read2st64_b32 v[76:77], v102 offset0:4 offset1:5
	v_mul_f32_e32 v103, v83, v78
	v_fma_f32 v103, v82, v79, -v103
	s_waitcnt lgkmcnt(0)
	v_add_f32_e32 v103, v76, v103
	v_mul_f32_e32 v76, v82, v78
	v_fmac_f32_e32 v76, v83, v79
	v_add_f32_e32 v78, v76, v77
	v_cvt_pk_bf16_f32 v76, v103, s0
	ds_write_b16 v86, v76 offset:8992
	v_cvt_pk_bf16_f32 v76, v78, s0
	ds_write_b16 v86, v76 offset:9120
	ds_read2_b32 v[76:77], v87 offset0:132 offset1:196
	v_mul_f32_e32 v79, v83, v78
	v_fma_f32 v79, v82, v103, -v79
	s_waitcnt lgkmcnt(0)
	v_add_f32_e32 v79, v76, v79
	v_mul_f32_e32 v76, v82, v78
	v_fmac_f32_e32 v76, v83, v103
	v_add_f32_e32 v78, v76, v77
	v_cvt_pk_bf16_f32 v76, v79, s0
	ds_write_b16 v86, v76 offset:8720
	v_cvt_pk_bf16_f32 v76, v78, s0
	ds_write_b16 v86, v76 offset:8848
	ds_read2st64_b32 v[76:77], v87 offset1:1
	v_mul_f32_e32 v103, v83, v78
	v_fma_f32 v103, v82, v79, -v103
	s_waitcnt lgkmcnt(0)
	v_add_f32_e32 v103, v76, v103
	v_mul_f32_e32 v76, v82, v78
	v_fmac_f32_e32 v76, v83, v79
	v_add_f32_e32 v108, v76, v77
	v_cvt_pk_bf16_f32 v76, v103, s0
	ds_write_b16 v86, v76 offset:8448
	v_cvt_pk_bf16_f32 v76, v108, s0
	ds_write_b16 v86, v76 offset:8576
	s_waitcnt vmcnt(0) lgkmcnt(0)
	ds_read_b128 v[76:79], v81 offset:8448
	ds_read_b128 v[104:107], v81 offset:8512
	s_waitcnt lgkmcnt(1)
	v_mfma_f32_16x16x32_bf16 v[76:79], v[76:79], v[32:35], 0
	s_waitcnt lgkmcnt(0)
	v_mfma_f32_16x16x32_bf16 v[76:79], v[104:107], v[28:31], v[76:79]
	ds_read_b128 v[104:107], v81 offset:8576
	s_waitcnt lgkmcnt(0)
	v_mfma_f32_16x16x32_bf16 v[76:79], v[104:107], v[24:27], v[76:79]
	ds_read_b128 v[104:107], v81 offset:8640
	ds_write2_b32 v88, v40, v36 offset1:16
	ds_write2_b32 v88, v41, v37 offset0:132 offset1:148
	ds_write2_b32 v89, v42, v38 offset0:8 offset1:24
	ds_write2_b32 v89, v43, v39 offset0:140 offset1:156
	v_mfma_f32_16x16x32_bf16 v[36:39], v[68:71], v[48:51], 0
	v_mfma_f32_16x16x32_bf16 v[40:43], v[68:71], v[44:47], 0
	s_nop 7
	ds_write2_b32 v88, v36, v40 offset0:32 offset1:48
	ds_write2_b32 v88, v37, v41 offset0:164 offset1:180
	ds_write2_b32 v89, v38, v42 offset0:40 offset1:56
	ds_write2_b32 v89, v39, v43 offset0:172 offset1:188
	v_mfma_f32_16x16x32_bf16 v[36:39], v[68:71], v[56:59], 0
	v_mfma_f32_16x16x32_bf16 v[40:43], v[68:71], v[52:55], 0
	s_nop 7
	ds_write2_b32 v88, v36, v40 offset0:64 offset1:80
	ds_write2_b32 v88, v37, v41 offset0:196 offset1:212
	ds_write2_b32 v89, v38, v42 offset0:72 offset1:88
	ds_write2_b32 v89, v39, v43 offset0:204 offset1:220
	v_mfma_f32_16x16x32_bf16 v[36:39], v[68:71], v[64:67], 0
	v_mfma_f32_16x16x32_bf16 v[40:43], v[68:71], v[60:63], 0
	s_nop 7
	ds_write2_b32 v88, v36, v40 offset0:96 offset1:112
	ds_write2_b32 v88, v37, v41 offset0:228 offset1:244
	ds_write2_b32 v89, v38, v42 offset0:104 offset1:120
	ds_write2_b32 v89, v39, v43 offset0:236 offset1:252
	s_waitcnt vmcnt(0) lgkmcnt(0)
	ds_read2st64_b32 v[36:37], v91 offset0:30 offset1:31
	v_mul_f32_e32 v38, v83, v108
	v_fma_f32 v38, v82, v103, -v38
	s_waitcnt lgkmcnt(14)
	v_mfma_f32_16x16x32_bf16 v[76:79], v[104:107], v[20:23], v[76:79]
	s_waitcnt lgkmcnt(0)
	v_add_f32_e32 v38, v38, v36
	v_mul_f32_e32 v36, v82, v108
	v_fmac_f32_e32 v36, v83, v103
	v_add_f32_e32 v39, v36, v37
	v_cvt_pk_bf16_f32 v36, v38, s0
	ds_write_b16 v86, v36 offset:12528
	v_cvt_pk_bf16_f32 v36, v39, s0
	ds_write_b16 v86, v36 offset:12656
	ds_read2st64_b32 v[36:37], v84 offset0:28 offset1:29
	v_mul_f32_e32 v40, v83, v39
	v_fma_f32 v40, v82, v38, -v40
	s_waitcnt lgkmcnt(0)
	v_add_f32_e32 v40, v36, v40
	v_mul_f32_e32 v36, v82, v39
	v_fmac_f32_e32 v36, v83, v38
	v_add_f32_e32 v38, v36, v37
	v_cvt_pk_bf16_f32 v36, v40, s0
	ds_write_b16 v86, v36 offset:12256
	v_cvt_pk_bf16_f32 v36, v38, s0
	ds_write_b16 v86, v36 offset:12384
	ds_read2st64_b32 v[36:37], v85 offset0:26 offset1:27
	v_mul_f32_e32 v39, v83, v38
	v_fma_f32 v39, v82, v40, -v39
	s_waitcnt lgkmcnt(0)
	v_add_f32_e32 v39, v36, v39
	v_mul_f32_e32 v36, v82, v38
	v_fmac_f32_e32 v36, v83, v40
	v_add_f32_e32 v38, v36, v37
	v_cvt_pk_bf16_f32 v36, v39, s0
	ds_write_b16 v86, v36 offset:11984
	v_cvt_pk_bf16_f32 v36, v38, s0
	ds_write_b16 v86, v36 offset:12112
	ds_read2st64_b32 v[36:37], v92 offset0:24 offset1:25
	v_mul_f32_e32 v40, v83, v38
	v_fma_f32 v40, v82, v39, -v40
	s_waitcnt lgkmcnt(0)
	v_add_f32_e32 v40, v36, v40
	v_mul_f32_e32 v36, v82, v38
	v_fmac_f32_e32 v36, v83, v39
	v_add_f32_e32 v38, v36, v37
	v_cvt_pk_bf16_f32 v36, v40, s0
	ds_write_b16 v86, v36 offset:11712
	v_cvt_pk_bf16_f32 v36, v38, s0
	ds_write_b16 v86, v36 offset:11840
	ds_read2st64_b32 v[36:37], v93 offset0:22 offset1:23
	v_mul_f32_e32 v39, v83, v38
	v_fma_f32 v39, v82, v40, -v39
	s_waitcnt lgkmcnt(0)
	v_add_f32_e32 v39, v36, v39
	v_mul_f32_e32 v36, v82, v38
	v_fmac_f32_e32 v36, v83, v40
	v_add_f32_e32 v38, v36, v37
	v_cvt_pk_bf16_f32 v36, v39, s0
	ds_write_b16 v86, v36 offset:11440
	v_cvt_pk_bf16_f32 v36, v38, s0
	ds_write_b16 v86, v36 offset:11568
	ds_read2st64_b32 v[36:37], v94 offset0:20 offset1:21
	v_mul_f32_e32 v40, v83, v38
	v_fma_f32 v40, v82, v39, -v40
	s_waitcnt lgkmcnt(0)
	v_add_f32_e32 v40, v36, v40
	v_mul_f32_e32 v36, v82, v38
	v_fmac_f32_e32 v36, v83, v39
	v_add_f32_e32 v38, v36, v37
	v_cvt_pk_bf16_f32 v36, v40, s0
	ds_write_b16 v86, v36 offset:11168
	v_cvt_pk_bf16_f32 v36, v38, s0
	ds_write_b16 v86, v36 offset:11296
	ds_read2st64_b32 v[36:37], v95 offset0:18 offset1:19
	v_mul_f32_e32 v39, v83, v38
	v_fma_f32 v39, v82, v40, -v39
	s_waitcnt lgkmcnt(0)
	v_add_f32_e32 v39, v36, v39
	v_mul_f32_e32 v36, v82, v38
	v_fmac_f32_e32 v36, v83, v40
	v_add_f32_e32 v38, v36, v37
	v_cvt_pk_bf16_f32 v36, v39, s0
	ds_write_b16 v86, v36 offset:10896
	v_cvt_pk_bf16_f32 v36, v38, s0
	ds_write_b16 v86, v36 offset:11024
	ds_read2st64_b32 v[36:37], v96 offset0:16 offset1:17
	v_mul_f32_e32 v40, v83, v38
	v_fma_f32 v40, v82, v39, -v40
	s_waitcnt lgkmcnt(0)
	v_add_f32_e32 v40, v36, v40
	v_mul_f32_e32 v36, v82, v38
	v_fmac_f32_e32 v36, v83, v39
	v_add_f32_e32 v38, v36, v37
	v_cvt_pk_bf16_f32 v36, v40, s0
	ds_write_b16 v86, v36 offset:10624
	v_cvt_pk_bf16_f32 v36, v38, s0
	ds_write_b16 v86, v36 offset:10752
	ds_read2st64_b32 v[36:37], v97 offset0:14 offset1:15
	v_mul_f32_e32 v39, v83, v38
	v_fma_f32 v39, v82, v40, -v39
	s_waitcnt lgkmcnt(0)
	v_add_f32_e32 v39, v36, v39
	v_mul_f32_e32 v36, v82, v38
	v_fmac_f32_e32 v36, v83, v40
	v_add_f32_e32 v38, v36, v37
	v_cvt_pk_bf16_f32 v36, v39, s0
	ds_write_b16 v86, v36 offset:10352
	v_cvt_pk_bf16_f32 v36, v38, s0
	ds_write_b16 v86, v36 offset:10480
	ds_read2st64_b32 v[36:37], v98 offset0:12 offset1:13
	v_mul_f32_e32 v40, v83, v38
	v_fma_f32 v40, v82, v39, -v40
	s_waitcnt lgkmcnt(0)
	v_add_f32_e32 v40, v36, v40
	v_mul_f32_e32 v36, v82, v38
	v_fmac_f32_e32 v36, v83, v39
	v_add_f32_e32 v38, v36, v37
	v_cvt_pk_bf16_f32 v36, v40, s0
	ds_write_b16 v86, v36 offset:10080
	v_cvt_pk_bf16_f32 v36, v38, s0
	ds_write_b16 v86, v36 offset:10208
	ds_read2st64_b32 v[36:37], v99 offset0:10 offset1:11
	v_mul_f32_e32 v39, v83, v38
	v_fma_f32 v39, v82, v40, -v39
	s_waitcnt lgkmcnt(0)
	v_add_f32_e32 v39, v36, v39
	v_mul_f32_e32 v36, v82, v38
	v_fmac_f32_e32 v36, v83, v40
	v_add_f32_e32 v38, v36, v37
	v_cvt_pk_bf16_f32 v36, v39, s0
	ds_write_b16 v86, v36 offset:9808
	v_cvt_pk_bf16_f32 v36, v38, s0
	ds_write_b16 v86, v36 offset:9936
	ds_read2st64_b32 v[36:37], v100 offset0:8 offset1:9
	v_mul_f32_e32 v40, v83, v38
	v_fma_f32 v40, v82, v39, -v40
	s_waitcnt lgkmcnt(0)
	v_add_f32_e32 v40, v36, v40
	v_mul_f32_e32 v36, v82, v38
	v_fmac_f32_e32 v36, v83, v39
	v_add_f32_e32 v38, v36, v37
	v_cvt_pk_bf16_f32 v36, v40, s0
	ds_write_b16 v86, v36 offset:9536
	v_cvt_pk_bf16_f32 v36, v38, s0
	ds_write_b16 v86, v36 offset:9664
	ds_read2st64_b32 v[36:37], v101 offset0:6 offset1:7
	v_mul_f32_e32 v39, v83, v38
	v_fma_f32 v39, v82, v40, -v39
	s_waitcnt lgkmcnt(0)
	v_add_f32_e32 v39, v36, v39
	v_mul_f32_e32 v36, v82, v38
	v_fmac_f32_e32 v36, v83, v40
	v_add_f32_e32 v38, v36, v37
	v_cvt_pk_bf16_f32 v36, v39, s0
	ds_write_b16 v86, v36 offset:9264
	v_cvt_pk_bf16_f32 v36, v38, s0
	ds_write_b16 v86, v36 offset:9392
	ds_read2st64_b32 v[36:37], v102 offset0:4 offset1:5
	v_mul_f32_e32 v40, v83, v38
	v_fma_f32 v40, v82, v39, -v40
	s_waitcnt lgkmcnt(0)
	v_add_f32_e32 v40, v36, v40
	v_mul_f32_e32 v36, v82, v38
	v_fmac_f32_e32 v36, v83, v39
	v_add_f32_e32 v38, v36, v37
	v_cvt_pk_bf16_f32 v36, v40, s0
	ds_write_b16 v86, v36 offset:8992
	v_cvt_pk_bf16_f32 v36, v38, s0
	ds_write_b16 v86, v36 offset:9120
	ds_read2_b32 v[36:37], v87 offset0:132 offset1:196
	v_mul_f32_e32 v39, v83, v38
	v_fma_f32 v39, v82, v40, -v39
	s_waitcnt lgkmcnt(0)
	v_add_f32_e32 v39, v36, v39
	v_mul_f32_e32 v36, v82, v38
	v_fmac_f32_e32 v36, v83, v40
	v_add_f32_e32 v38, v36, v37
	v_cvt_pk_bf16_f32 v36, v39, s0
	ds_write_b16 v86, v36 offset:8720
	v_cvt_pk_bf16_f32 v36, v38, s0
	ds_write_b16 v86, v36 offset:8848
	ds_read2st64_b32 v[36:37], v87 offset1:1
	v_mul_f32_e32 v40, v83, v38
	v_fma_f32 v40, v82, v39, -v40
	v_mul_f32_e32 v38, v82, v38
	v_fmac_f32_e32 v38, v83, v39
	s_waitcnt lgkmcnt(0)
	v_add_f32_e32 v36, v36, v40
	v_add_f32_e32 v37, v38, v37
	v_cvt_pk_bf16_f32 v36, v36, s0
	ds_write_b16 v86, v36 offset:8448
	v_cvt_pk_bf16_f32 v36, v37, s0
	ds_write_b16 v86, v36 offset:8576
	s_waitcnt vmcnt(0) lgkmcnt(0)
	ds_read_b128 v[36:39], v81 offset:8448
	s_waitcnt lgkmcnt(0)
	v_mfma_f32_16x16x32_bf16 v[32:35], v[36:39], v[32:35], 0
	ds_read_b128 v[36:39], v81 offset:8512
	s_waitcnt lgkmcnt(0)
	v_mfma_f32_16x16x32_bf16 v[28:31], v[36:39], v[28:31], v[32:35]
	s_nop 4
	ds_read_b128 v[32:35], v81 offset:8576
	s_waitcnt lgkmcnt(0)
	v_mfma_f32_16x16x32_bf16 v[24:27], v[32:35], v[24:27], v[28:31]
	s_nop 2
	ds_read_b128 v[28:31], v81 offset:8640
	s_waitcnt lgkmcnt(0)
	v_mfma_f32_16x16x32_bf16 v[20:23], v[28:31], v[20:23], v[24:27]
	s_nop 7
	v_pk_add_f32 v[24:25], v[0:1], v[20:21]
	v_and_or_b32 v0, v90, 15, v80
	v_add_u32_e32 v20, s6, v0
	v_ashrrev_i32_e32 v21, 31, v20
	v_lshrrev_b32_e32 v1, 2, v90
	v_lshl_add_u64 v[20:21], v[20:21], 2, s[76:77]
	v_and_b32_e32 v1, 12, v1
	global_load_dword v28, v[20:21], off
	v_add_u32_e32 v20, s8, v1
	v_ashrrev_i32_e32 v21, 31, v20
	v_ashrrev_i32_e32 v1, 31, v0
	v_lshlrev_b64 v[26:27], 9, v[20:21]
	v_lshl_add_u64 v[26:27], v[26:27], 0, v[0:1]
	v_lshl_add_u64 v[30:31], v[26:27], 1, s[36:37]
	global_load_ushort v29, v[30:31], off
	global_load_ushort v141, v[30:31], off offset:1024
	global_load_ushort v142, v[30:31], off offset:2048
	global_load_ushort v143, v[30:31], off offset:3072
	s_mov_b64 s[0:1], 0x4000
	v_lshl_add_u64 v[156:157], v[30:31], 0, s[0:1]
	global_load_ushort v144, v[156:157], off
	global_load_ushort v145, v[156:157], off offset:1024
	global_load_ushort v146, v[156:157], off offset:2048
	global_load_ushort v147, v[156:157], off offset:3072
	s_mov_b64 s[0:1], 0x8000
	v_lshl_add_u64 v[158:159], v[30:31], 0, s[0:1]
	global_load_ushort v148, v[158:159], off
	global_load_ushort v149, v[158:159], off offset:1024
	global_load_ushort v150, v[158:159], off offset:2048
	global_load_ushort v151, v[158:159], off offset:3072
	s_mov_b64 s[0:1], 0xc000
	v_lshl_add_u64 v[160:161], v[30:31], 0, s[0:1]
	global_load_ushort v152, v[160:161], off
	global_load_ushort v153, v[160:161], off offset:1024
	global_load_ushort v154, v[160:161], off offset:2048
	global_load_ushort v155, v[160:161], off offset:3072
	s_waitcnt vmcnt(0) lgkmcnt(0)
	v_lshlrev_b32_e32 v29, 16, v29
	v_fma_f32 v24, v28, v29, v24
	v_mul_f32_e32 v29, 0x3d372713, v24
	v_mul_f32_e32 v29, v24, v29
	v_fma_f32 v29, v24, v29, v24
	v_mul_f32_e32 v29, 0x3f4c422a, v29
	v_cmp_nlt_f32_e64 s[0:1], |v29|, s10
	s_and_saveexec_b64 s[2:3], s[0:1]
	s_xor_b64 s[0:1], exec, s[2:3]
	s_cbranch_execz .LBB0_1813
	v_add_f32_e64 v30, |v29|, |v29|
	v_mul_f32_e32 v31, 0x3fb8aa3b, v30
	v_rndne_f32_e32 v32, v31
	s_mov_b32 s2, 0x3fb8aa3b
	v_sub_f32_e32 v33, v31, v32
	v_fma_f32 v31, v30, s2, -v31
	v_fmac_f32_e32 v31, 0x32a5705f, v30
	v_add_f32_e32 v31, v33, v31
	v_cvt_i32_f32_e32 v32, v32
	v_exp_f32_e32 v31, v31
	s_mov_b32 s2, 0xc2ce8ed0
	v_cmp_ngt_f32_e32 vcc, s2, v30
	s_mov_b32 s2, 0x42b17218
	v_ldexp_f32 v31, v31, v32
	v_cndmask_b32_e32 v31, 0, v31, vcc
	v_cmp_nlt_f32_e32 vcc, s2, v30
	s_nop 1
	v_cndmask_b32_e32 v30, v235, v31, vcc
	v_add_f32_e32 v30, 1.0, v30
	v_rcp_f32_e32 v30, v30
	s_nop 0
	v_fma_f32 v30, v30, -2.0, 1.0
.LBB0_1813:
	s_andn2_saveexec_b64 s[0:1], s[0:1]
	v_mul_f32_e32 v30, v29, v29
	v_fmamk_f32 v31, v30, 0xbbbac73d, v204
	v_fmaak_f32 v31, v30, v31, 0xbd5c1c4e
	v_fmaak_f32 v31, v30, v31, 0x3e088382
	v_fmaak_f32 v31, v30, v31, 0xbeaaaa99
	v_mul_f32_e64 v31, |v29|, v31
	v_fma_f32 v30, v30, v31, |v29|
	s_or_b64 exec, exec, s[0:1]
	s_brev_b32 s0, -2
	v_bfi_b32 v29, s0, v30, v29
	v_mul_f32_e32 v24, 0.5, v24
	v_add_f32_e32 v29, 1.0, v29
	v_mul_f32_e32 v24, v24, v29
	v_cvt_pk_bf16_f32 v24, v24, s0
	v_lshl_add_u64 v[26:27], v[26:27], 1, s[44:45]
	global_store_short v[26:27], v24, off
	v_lshlrev_b64 v[26:27], 9, v[20:21]
	v_lshl_add_u64 v[26:27], v[26:27], 0, v[0:1]
	s_mov_b64 s[0:1], 0x200
	v_lshl_add_u64 v[26:27], v[26:27], 0, s[0:1]
	v_lshl_add_u64 v[30:31], v[26:27], 1, s[36:37]
	v_mov_b32_e32 v24, v141
	v_pk_add_f32 v[2:3], v[2:3], 0 op_sel_hi:[1,0]
	s_nop 0
	v_pk_add_f32 v[2:3], v[2:3], v[22:23]
	v_lshlrev_b32_e32 v22, 16, v24
	v_fmac_f32_e32 v25, v28, v22
	v_mul_f32_e32 v22, 0x3d372713, v25
	v_mul_f32_e32 v22, v25, v22
	v_fma_f32 v22, v25, v22, v25
	v_mul_f32_e32 v22, 0x3f4c422a, v22
	v_cmp_nlt_f32_e64 s[0:1], |v22|, s10
	s_and_saveexec_b64 s[2:3], s[0:1]
	s_xor_b64 s[0:1], exec, s[2:3]
	s_cbranch_execz .LBB0_1817
	v_add_f32_e64 v23, |v22|, |v22|
	v_mul_f32_e32 v24, 0x3fb8aa3b, v23
	v_rndne_f32_e32 v29, v24
	s_mov_b32 s2, 0x3fb8aa3b
	v_sub_f32_e32 v30, v24, v29
	v_fma_f32 v24, v23, s2, -v24
	v_fmac_f32_e32 v24, 0x32a5705f, v23
	v_add_f32_e32 v24, v30, v24
	v_cvt_i32_f32_e32 v29, v29
	v_exp_f32_e32 v24, v24
	s_mov_b32 s2, 0xc2ce8ed0
	v_cmp_ngt_f32_e32 vcc, s2, v23
	s_mov_b32 s2, 0x42b17218
	v_ldexp_f32 v24, v24, v29
	v_cndmask_b32_e32 v24, 0, v24, vcc
	v_cmp_nlt_f32_e32 vcc, s2, v23
	s_nop 1
	v_cndmask_b32_e32 v23, v235, v24, vcc
	v_add_f32_e32 v23, 1.0, v23
	v_rcp_f32_e32 v23, v23
	s_nop 0
	v_fma_f32 v23, v23, -2.0, 1.0
.LBB0_1817:
	s_andn2_saveexec_b64 s[0:1], s[0:1]
	v_mul_f32_e32 v23, v22, v22
	v_fmamk_f32 v24, v23, 0xbbbac73d, v204
	v_fmaak_f32 v24, v23, v24, 0xbd5c1c4e
	v_fmaak_f32 v24, v23, v24, 0x3e088382
	v_fmaak_f32 v24, v23, v24, 0xbeaaaa99
	v_mul_f32_e64 v24, |v22|, v24
	v_fma_f32 v23, v23, v24, |v22|
	s_or_b64 exec, exec, s[0:1]
	s_brev_b32 s0, -2
	v_bfi_b32 v22, s0, v23, v22
	v_mul_f32_e32 v24, 0.5, v25
	v_add_f32_e32 v22, 1.0, v22
	v_mul_f32_e32 v22, v24, v22
	v_cvt_pk_bf16_f32 v24, v22, s0
	v_lshl_add_u64 v[22:23], v[26:27], 1, s[44:45]
	global_store_short v[22:23], v24, off
	v_lshlrev_b64 v[22:23], 9, v[20:21]
	v_lshl_add_u64 v[22:23], v[22:23], 0, v[0:1]
	s_mov_b64 s[0:1], 0x400
	v_lshl_add_u64 v[22:23], v[22:23], 0, s[0:1]
	v_lshl_add_u64 v[24:25], v[22:23], 1, s[36:37]
	v_mov_b32_e32 v24, v142
	v_lshlrev_b32_e32 v24, 16, v24
	v_fma_f32 v2, v28, v24, v2
	v_mul_f32_e32 v24, 0x3d372713, v2
	v_mul_f32_e32 v24, v2, v24
	v_fma_f32 v24, v2, v24, v2
	v_mul_f32_e32 v24, 0x3f4c422a, v24
	v_cmp_nlt_f32_e64 s[0:1], |v24|, s10
	s_and_saveexec_b64 s[2:3], s[0:1]
	s_xor_b64 s[0:1], exec, s[2:3]
	s_cbranch_execz .LBB0_1821
	v_add_f32_e64 v25, |v24|, |v24|
	v_mul_f32_e32 v26, 0x3fb8aa3b, v25
	v_rndne_f32_e32 v27, v26
	s_mov_b32 s2, 0x3fb8aa3b
	v_sub_f32_e32 v29, v26, v27
	v_fma_f32 v26, v25, s2, -v26
	v_fmac_f32_e32 v26, 0x32a5705f, v25
	v_add_f32_e32 v26, v29, v26
	v_cvt_i32_f32_e32 v27, v27
	v_exp_f32_e32 v26, v26
	s_mov_b32 s2, 0xc2ce8ed0
	v_cmp_ngt_f32_e32 vcc, s2, v25
	s_mov_b32 s2, 0x42b17218
	v_ldexp_f32 v26, v26, v27
	v_cndmask_b32_e32 v26, 0, v26, vcc
	v_cmp_nlt_f32_e32 vcc, s2, v25
	s_nop 1
	v_cndmask_b32_e32 v25, v235, v26, vcc
	v_add_f32_e32 v25, 1.0, v25
	v_rcp_f32_e32 v25, v25
	s_nop 0
	v_fma_f32 v25, v25, -2.0, 1.0
.LBB0_1821:
	s_andn2_saveexec_b64 s[0:1], s[0:1]
	v_mul_f32_e32 v25, v24, v24
	v_fmamk_f32 v26, v25, 0xbbbac73d, v204
	v_fmaak_f32 v26, v25, v26, 0xbd5c1c4e
	v_fmaak_f32 v26, v25, v26, 0x3e088382
	v_fmaak_f32 v26, v25, v26, 0xbeaaaa99
	v_mul_f32_e64 v26, |v24|, v26
	v_fma_f32 v25, v25, v26, |v24|
	s_or_b64 exec, exec, s[0:1]
	s_brev_b32 s0, -2
	v_bfi_b32 v24, s0, v25, v24
	v_mul_f32_e32 v2, 0.5, v2
	v_add_f32_e32 v24, 1.0, v24
	v_mul_f32_e32 v2, v2, v24
	v_cvt_pk_bf16_f32 v2, v2, s0
	v_lshl_add_u64 v[22:23], v[22:23], 1, s[44:45]
	global_store_short v[22:23], v2, off
	v_lshlrev_b64 v[22:23], 9, v[20:21]
	v_lshl_add_u64 v[22:23], v[22:23], 0, v[0:1]
	s_mov_b64 s[0:1], 0x600
	v_lshl_add_u64 v[22:23], v[22:23], 0, s[0:1]
	v_lshl_add_u64 v[24:25], v[22:23], 1, s[36:37]
	v_mov_b32_e32 v2, v143
	v_lshlrev_b32_e32 v2, 16, v2
	v_fmac_f32_e32 v3, v28, v2
	v_mul_f32_e32 v2, 0x3d372713, v3
	v_mul_f32_e32 v2, v3, v2
	v_fma_f32 v2, v3, v2, v3
	v_mul_f32_e32 v2, 0x3f4c422a, v2
	v_cmp_nlt_f32_e64 s[0:1], |v2|, s10
	s_and_saveexec_b64 s[2:3], s[0:1]
	s_xor_b64 s[0:1], exec, s[2:3]
	s_cbranch_execz .LBB0_1825
	v_add_f32_e64 v24, |v2|, |v2|
	v_mul_f32_e32 v25, 0x3fb8aa3b, v24
	v_rndne_f32_e32 v26, v25
	s_mov_b32 s2, 0x3fb8aa3b
	v_sub_f32_e32 v27, v25, v26
	v_fma_f32 v25, v24, s2, -v25
	v_fmac_f32_e32 v25, 0x32a5705f, v24
	v_add_f32_e32 v25, v27, v25
	v_cvt_i32_f32_e32 v26, v26
	v_exp_f32_e32 v25, v25
	s_mov_b32 s2, 0xc2ce8ed0
	v_cmp_ngt_f32_e32 vcc, s2, v24
	s_mov_b32 s2, 0x42b17218
	v_ldexp_f32 v25, v25, v26
	v_cndmask_b32_e32 v25, 0, v25, vcc
	v_cmp_nlt_f32_e32 vcc, s2, v24
	s_nop 1
	v_cndmask_b32_e32 v24, v235, v25, vcc
	v_add_f32_e32 v24, 1.0, v24
	v_rcp_f32_e32 v24, v24
	s_nop 0
	v_fma_f32 v24, v24, -2.0, 1.0
.LBB0_1825:
	s_andn2_saveexec_b64 s[0:1], s[0:1]
	v_mul_f32_e32 v24, v2, v2
	v_fmamk_f32 v25, v24, 0xbbbac73d, v204
	v_fmaak_f32 v25, v24, v25, 0xbd5c1c4e
	v_fmaak_f32 v25, v24, v25, 0x3e088382
	v_fmaak_f32 v25, v24, v25, 0xbeaaaa99
	v_mul_f32_e64 v25, |v2|, v25
	v_fma_f32 v24, v24, v25, |v2|
	s_or_b64 exec, exec, s[0:1]
	s_brev_b32 s0, -2
	v_bfi_b32 v2, s0, v24, v2
	v_mul_f32_e32 v3, 0.5, v3
	v_add_f32_e32 v2, 1.0, v2
	v_mul_f32_e32 v2, v3, v2
	v_cvt_pk_bf16_f32 v24, v2, s0
	v_lshl_add_u64 v[2:3], v[22:23], 1, s[44:45]
	global_store_short v[2:3], v24, off
	v_lshlrev_b64 v[2:3], 9, v[20:21]
	v_lshl_add_u64 v[2:3], v[2:3], 0, v[0:1]
	s_mov_b64 s[0:1], 0x2000
	v_lshl_add_u64 v[2:3], v[2:3], 0, s[0:1]
	v_lshl_add_u64 v[22:23], v[2:3], 1, s[36:37]
	v_mov_b32_e32 v22, v144
	v_pk_add_f32 v[4:5], v[4:5], 0 op_sel_hi:[1,0]
	v_lshlrev_b32_e32 v22, 16, v22
	v_pk_add_f32 v[4:5], v[4:5], v[76:77]
	s_nop 0
	v_fma_f32 v4, v28, v22, v4
	v_mul_f32_e32 v22, 0x3d372713, v4
	v_mul_f32_e32 v22, v4, v22
	v_fma_f32 v22, v4, v22, v4
	v_mul_f32_e32 v22, 0x3f4c422a, v22
	v_cmp_nlt_f32_e64 s[0:1], |v22|, s10
	s_and_saveexec_b64 s[2:3], s[0:1]
	s_xor_b64 s[0:1], exec, s[2:3]
	s_cbranch_execz .LBB0_1829
	v_add_f32_e64 v23, |v22|, |v22|
	v_mul_f32_e32 v24, 0x3fb8aa3b, v23
	v_rndne_f32_e32 v25, v24
	s_mov_b32 s2, 0x3fb8aa3b
	v_sub_f32_e32 v26, v24, v25
	v_fma_f32 v24, v23, s2, -v24
	v_fmac_f32_e32 v24, 0x32a5705f, v23
	v_add_f32_e32 v24, v26, v24
	v_cvt_i32_f32_e32 v25, v25
	v_exp_f32_e32 v24, v24
	s_mov_b32 s2, 0xc2ce8ed0
	v_cmp_ngt_f32_e32 vcc, s2, v23
	s_mov_b32 s2, 0x42b17218
	v_ldexp_f32 v24, v24, v25
	v_cndmask_b32_e32 v24, 0, v24, vcc
	v_cmp_nlt_f32_e32 vcc, s2, v23
	s_nop 1
	v_cndmask_b32_e32 v23, v235, v24, vcc
	v_add_f32_e32 v23, 1.0, v23
	v_rcp_f32_e32 v23, v23
	s_nop 0
	v_fma_f32 v23, v23, -2.0, 1.0
.LBB0_1829:
	s_andn2_saveexec_b64 s[0:1], s[0:1]
	v_mul_f32_e32 v23, v22, v22
	v_fmamk_f32 v24, v23, 0xbbbac73d, v204
	v_fmaak_f32 v24, v23, v24, 0xbd5c1c4e
	v_fmaak_f32 v24, v23, v24, 0x3e088382
	v_fmaak_f32 v24, v23, v24, 0xbeaaaa99
	v_mul_f32_e64 v24, |v22|, v24
	v_fma_f32 v23, v23, v24, |v22|
	s_or_b64 exec, exec, s[0:1]
	s_brev_b32 s0, -2
	v_bfi_b32 v22, s0, v23, v22
	v_mul_f32_e32 v4, 0.5, v4
	v_add_f32_e32 v22, 1.0, v22
	v_mul_f32_e32 v4, v4, v22
	v_cvt_pk_bf16_f32 v4, v4, s0
	v_lshl_add_u64 v[2:3], v[2:3], 1, s[44:45]
	global_store_short v[2:3], v4, off
	v_lshlrev_b64 v[2:3], 9, v[20:21]
	v_lshl_add_u64 v[2:3], v[2:3], 0, v[0:1]
	s_mov_b64 s[0:1], 0x2200
	v_lshl_add_u64 v[22:23], v[2:3], 0, s[0:1]
	v_lshl_add_u64 v[2:3], v[22:23], 1, s[36:37]
	v_mov_b32_e32 v4, v145
	v_pk_add_f32 v[2:3], v[6:7], 0 op_sel_hi:[1,0]
	v_lshlrev_b32_e32 v4, 16, v4
	v_fmac_f32_e32 v5, v28, v4
	v_mul_f32_e32 v4, 0x3d372713, v5
	v_mul_f32_e32 v4, v5, v4
	v_fma_f32 v4, v5, v4, v5
	v_mul_f32_e32 v4, 0x3f4c422a, v4
	v_pk_add_f32 v[2:3], v[2:3], v[78:79]
	v_cmp_nlt_f32_e64 s[0:1], |v4|, s10
	s_and_saveexec_b64 s[2:3], s[0:1]
	s_xor_b64 s[0:1], exec, s[2:3]
	s_cbranch_execz .LBB0_1833
	v_add_f32_e64 v6, |v4|, |v4|
	v_mul_f32_e32 v7, 0x3fb8aa3b, v6
	v_rndne_f32_e32 v24, v7
	s_mov_b32 s2, 0x3fb8aa3b
	v_sub_f32_e32 v25, v7, v24
	v_fma_f32 v7, v6, s2, -v7
	v_fmac_f32_e32 v7, 0x32a5705f, v6
	v_add_f32_e32 v7, v25, v7
	v_cvt_i32_f32_e32 v24, v24
	v_exp_f32_e32 v7, v7
	s_mov_b32 s2, 0xc2ce8ed0
	v_cmp_ngt_f32_e32 vcc, s2, v6
	s_mov_b32 s2, 0x42b17218
	v_ldexp_f32 v7, v7, v24
	v_cndmask_b32_e32 v7, 0, v7, vcc
	v_cmp_nlt_f32_e32 vcc, s2, v6
	s_nop 1
	v_cndmask_b32_e32 v6, v235, v7, vcc
	v_add_f32_e32 v6, 1.0, v6
	v_rcp_f32_e32 v6, v6
	s_nop 0
	v_fma_f32 v6, v6, -2.0, 1.0
.LBB0_1833:
	s_andn2_saveexec_b64 s[0:1], s[0:1]
	v_mul_f32_e32 v6, v4, v4
	v_fmamk_f32 v7, v6, 0xbbbac73d, v204
	v_fmaak_f32 v7, v6, v7, 0xbd5c1c4e
	v_fmaak_f32 v7, v6, v7, 0x3e088382
	v_fmaak_f32 v7, v6, v7, 0xbeaaaa99
	v_mul_f32_e64 v7, |v4|, v7
	v_fma_f32 v6, v6, v7, |v4|
	s_or_b64 exec, exec, s[0:1]
	s_brev_b32 s0, -2
	v_bfi_b32 v4, s0, v6, v4
	v_mul_f32_e32 v5, 0.5, v5
	v_add_f32_e32 v4, 1.0, v4
	v_mul_f32_e32 v4, v5, v4
	v_cvt_pk_bf16_f32 v6, v4, s0
	v_lshl_add_u64 v[4:5], v[22:23], 1, s[44:45]
	global_store_short v[4:5], v6, off
	v_lshlrev_b64 v[4:5], 9, v[20:21]
	v_lshl_add_u64 v[4:5], v[4:5], 0, v[0:1]
	s_mov_b64 s[0:1], 0x2400
	v_lshl_add_u64 v[4:5], v[4:5], 0, s[0:1]
	v_lshl_add_u64 v[6:7], v[4:5], 1, s[36:37]
	v_mov_b32_e32 v6, v146
	v_lshlrev_b32_e32 v6, 16, v6
	v_fma_f32 v2, v28, v6, v2
	v_mul_f32_e32 v6, 0x3d372713, v2
	v_mul_f32_e32 v6, v2, v6
	v_fma_f32 v6, v2, v6, v2
	v_mul_f32_e32 v6, 0x3f4c422a, v6
	v_cmp_nlt_f32_e64 s[0:1], |v6|, s10
	s_and_saveexec_b64 s[2:3], s[0:1]
	s_xor_b64 s[0:1], exec, s[2:3]
	s_cbranch_execz .LBB0_1837
	v_add_f32_e64 v7, |v6|, |v6|
	v_mul_f32_e32 v22, 0x3fb8aa3b, v7
	v_rndne_f32_e32 v23, v22
	s_mov_b32 s2, 0x3fb8aa3b
	v_sub_f32_e32 v24, v22, v23
	v_fma_f32 v22, v7, s2, -v22
	v_fmac_f32_e32 v22, 0x32a5705f, v7
	v_add_f32_e32 v22, v24, v22
	v_cvt_i32_f32_e32 v23, v23
	v_exp_f32_e32 v22, v22
	s_mov_b32 s2, 0xc2ce8ed0
	v_cmp_ngt_f32_e32 vcc, s2, v7
	s_mov_b32 s2, 0x42b17218
	v_ldexp_f32 v22, v22, v23
	v_cndmask_b32_e32 v22, 0, v22, vcc
	v_cmp_nlt_f32_e32 vcc, s2, v7
	s_nop 1
	v_cndmask_b32_e32 v7, v235, v22, vcc
	v_add_f32_e32 v7, 1.0, v7
	v_rcp_f32_e32 v7, v7
	s_nop 0
	v_fma_f32 v7, v7, -2.0, 1.0
.LBB0_1837:
	s_andn2_saveexec_b64 s[0:1], s[0:1]
	v_mul_f32_e32 v7, v6, v6
	v_fmamk_f32 v22, v7, 0xbbbac73d, v204
	v_fmaak_f32 v22, v7, v22, 0xbd5c1c4e
	v_fmaak_f32 v22, v7, v22, 0x3e088382
	v_fmaak_f32 v22, v7, v22, 0xbeaaaa99
	v_mul_f32_e64 v22, |v6|, v22
	v_fma_f32 v7, v7, v22, |v6|
	s_or_b64 exec, exec, s[0:1]
	s_brev_b32 s0, -2
	v_bfi_b32 v6, s0, v7, v6
	v_mul_f32_e32 v2, 0.5, v2
	v_add_f32_e32 v6, 1.0, v6
	v_mul_f32_e32 v2, v2, v6
	v_cvt_pk_bf16_f32 v2, v2, s0
	v_lshl_add_u64 v[4:5], v[4:5], 1, s[44:45]
	global_store_short v[4:5], v2, off
	v_lshlrev_b64 v[4:5], 9, v[20:21]
	v_lshl_add_u64 v[4:5], v[4:5], 0, v[0:1]
	s_mov_b64 s[0:1], 0x2600
	v_lshl_add_u64 v[4:5], v[4:5], 0, s[0:1]
	v_lshl_add_u64 v[6:7], v[4:5], 1, s[36:37]
	v_mov_b32_e32 v2, v147
	v_lshlrev_b32_e32 v2, 16, v2
	v_fmac_f32_e32 v3, v28, v2
	v_mul_f32_e32 v2, 0x3d372713, v3
	v_mul_f32_e32 v2, v3, v2
	v_fma_f32 v2, v3, v2, v3
	v_mul_f32_e32 v2, 0x3f4c422a, v2
	v_cmp_nlt_f32_e64 s[0:1], |v2|, s10
	s_and_saveexec_b64 s[2:3], s[0:1]
	s_xor_b64 s[0:1], exec, s[2:3]
	s_cbranch_execz .LBB0_1841
	v_add_f32_e64 v6, |v2|, |v2|
	v_mul_f32_e32 v7, 0x3fb8aa3b, v6
	v_rndne_f32_e32 v22, v7
	s_mov_b32 s2, 0x3fb8aa3b
	v_sub_f32_e32 v23, v7, v22
	v_fma_f32 v7, v6, s2, -v7
	v_fmac_f32_e32 v7, 0x32a5705f, v6
	v_add_f32_e32 v7, v23, v7
	v_cvt_i32_f32_e32 v22, v22
	v_exp_f32_e32 v7, v7
	s_mov_b32 s2, 0xc2ce8ed0
	v_cmp_ngt_f32_e32 vcc, s2, v6
	s_mov_b32 s2, 0x42b17218
	v_ldexp_f32 v7, v7, v22
	v_cndmask_b32_e32 v7, 0, v7, vcc
	v_cmp_nlt_f32_e32 vcc, s2, v6
	s_nop 1
	v_cndmask_b32_e32 v6, v235, v7, vcc
	v_add_f32_e32 v6, 1.0, v6
	v_rcp_f32_e32 v6, v6
	s_nop 0
	v_fma_f32 v6, v6, -2.0, 1.0
.LBB0_1841:
	s_andn2_saveexec_b64 s[0:1], s[0:1]
	v_mul_f32_e32 v6, v2, v2
	v_fmamk_f32 v7, v6, 0xbbbac73d, v204
	v_fmaak_f32 v7, v6, v7, 0xbd5c1c4e
	v_fmaak_f32 v7, v6, v7, 0x3e088382
	v_fmaak_f32 v7, v6, v7, 0xbeaaaa99
	v_mul_f32_e64 v7, |v2|, v7
	v_fma_f32 v6, v6, v7, |v2|
	s_or_b64 exec, exec, s[0:1]
	s_brev_b32 s0, -2
	v_bfi_b32 v2, s0, v6, v2
	v_mul_f32_e32 v3, 0.5, v3
	v_add_f32_e32 v2, 1.0, v2
	v_mul_f32_e32 v2, v3, v2
	v_cvt_pk_bf16_f32 v6, v2, s0
	v_lshl_add_u64 v[2:3], v[4:5], 1, s[44:45]
	global_store_short v[2:3], v6, off
	v_lshlrev_b64 v[2:3], 9, v[20:21]
	v_lshl_add_u64 v[2:3], v[2:3], 0, v[0:1]
	s_mov_b64 s[0:1], 0x4000
	v_lshl_add_u64 v[2:3], v[2:3], 0, s[0:1]
	v_lshl_add_u64 v[4:5], v[2:3], 1, s[36:37]
	v_mov_b32_e32 v6, v148
	v_pk_add_f32 v[4:5], v[8:9], 0 op_sel_hi:[1,0]
	v_lshlrev_b32_e32 v6, 16, v6
	v_pk_add_f32 v[4:5], v[4:5], v[72:73]
	s_nop 0
	v_fma_f32 v4, v28, v6, v4
	v_mul_f32_e32 v6, 0x3d372713, v4
	v_mul_f32_e32 v6, v4, v6
	v_fma_f32 v6, v4, v6, v4
	v_mul_f32_e32 v6, 0x3f4c422a, v6
	v_cmp_nlt_f32_e64 s[0:1], |v6|, s10
	s_and_saveexec_b64 s[2:3], s[0:1]
	s_xor_b64 s[0:1], exec, s[2:3]
	s_cbranch_execz .LBB0_1845
	v_add_f32_e64 v7, |v6|, |v6|
	v_mul_f32_e32 v8, 0x3fb8aa3b, v7
	v_rndne_f32_e32 v9, v8
	s_mov_b32 s2, 0x3fb8aa3b
	v_sub_f32_e32 v22, v8, v9
	v_fma_f32 v8, v7, s2, -v8
	v_fmac_f32_e32 v8, 0x32a5705f, v7
	v_add_f32_e32 v8, v22, v8
	v_cvt_i32_f32_e32 v9, v9
	v_exp_f32_e32 v8, v8
	s_mov_b32 s2, 0xc2ce8ed0
	v_cmp_ngt_f32_e32 vcc, s2, v7
	s_mov_b32 s2, 0x42b17218
	v_ldexp_f32 v8, v8, v9
	v_cndmask_b32_e32 v8, 0, v8, vcc
	v_cmp_nlt_f32_e32 vcc, s2, v7
	s_nop 1
	v_cndmask_b32_e32 v7, v235, v8, vcc
	v_add_f32_e32 v7, 1.0, v7
	v_rcp_f32_e32 v7, v7
	s_nop 0
	v_fma_f32 v7, v7, -2.0, 1.0
.LBB0_1845:
	s_andn2_saveexec_b64 s[0:1], s[0:1]
	v_mul_f32_e32 v7, v6, v6
	v_fmamk_f32 v8, v7, 0xbbbac73d, v204
	v_fmaak_f32 v8, v7, v8, 0xbd5c1c4e
	v_fmaak_f32 v8, v7, v8, 0x3e088382
	v_fmaak_f32 v8, v7, v8, 0xbeaaaa99
	v_mul_f32_e64 v8, |v6|, v8
	v_fma_f32 v7, v7, v8, |v6|
	s_or_b64 exec, exec, s[0:1]
	s_brev_b32 s0, -2
	v_bfi_b32 v6, s0, v7, v6
	v_mul_f32_e32 v4, 0.5, v4
	v_add_f32_e32 v6, 1.0, v6
	v_mul_f32_e32 v4, v4, v6
	v_cvt_pk_bf16_f32 v4, v4, s0
	v_lshl_add_u64 v[2:3], v[2:3], 1, s[44:45]
	global_store_short v[2:3], v4, off
	v_lshlrev_b64 v[2:3], 9, v[20:21]
	v_lshl_add_u64 v[2:3], v[2:3], 0, v[0:1]
	s_mov_b64 s[0:1], 0x4200
	v_lshl_add_u64 v[6:7], v[2:3], 0, s[0:1]
	v_lshl_add_u64 v[2:3], v[6:7], 1, s[36:37]
	v_mov_b32_e32 v4, v149
	v_pk_add_f32 v[2:3], v[10:11], 0 op_sel_hi:[1,0]
	v_lshlrev_b32_e32 v4, 16, v4
	v_fmac_f32_e32 v5, v28, v4
	v_mul_f32_e32 v4, 0x3d372713, v5
	v_mul_f32_e32 v4, v5, v4
	v_fma_f32 v4, v5, v4, v5
	v_mul_f32_e32 v4, 0x3f4c422a, v4
	v_pk_add_f32 v[2:3], v[2:3], v[74:75]
	v_cmp_nlt_f32_e64 s[0:1], |v4|, s10
	s_and_saveexec_b64 s[2:3], s[0:1]
	s_xor_b64 s[0:1], exec, s[2:3]
	s_cbranch_execz .LBB0_1849
	v_add_f32_e64 v8, |v4|, |v4|
	v_mul_f32_e32 v9, 0x3fb8aa3b, v8
	v_rndne_f32_e32 v10, v9
	s_mov_b32 s2, 0x3fb8aa3b
	v_sub_f32_e32 v11, v9, v10
	v_fma_f32 v9, v8, s2, -v9
	v_fmac_f32_e32 v9, 0x32a5705f, v8
	v_add_f32_e32 v9, v11, v9
	v_cvt_i32_f32_e32 v10, v10
	v_exp_f32_e32 v9, v9
	s_mov_b32 s2, 0xc2ce8ed0
	v_cmp_ngt_f32_e32 vcc, s2, v8
	s_mov_b32 s2, 0x42b17218
	v_ldexp_f32 v9, v9, v10
	v_cndmask_b32_e32 v9, 0, v9, vcc
	v_cmp_nlt_f32_e32 vcc, s2, v8
	s_nop 1
	v_cndmask_b32_e32 v8, v235, v9, vcc
	v_add_f32_e32 v8, 1.0, v8
	v_rcp_f32_e32 v8, v8
	s_nop 0
	v_fma_f32 v8, v8, -2.0, 1.0
.LBB0_1849:
	s_andn2_saveexec_b64 s[0:1], s[0:1]
	v_mul_f32_e32 v8, v4, v4
	v_fmamk_f32 v9, v8, 0xbbbac73d, v204
	v_fmaak_f32 v9, v8, v9, 0xbd5c1c4e
	v_fmaak_f32 v9, v8, v9, 0x3e088382
	v_fmaak_f32 v9, v8, v9, 0xbeaaaa99
	v_mul_f32_e64 v9, |v4|, v9
	v_fma_f32 v8, v8, v9, |v4|
	s_or_b64 exec, exec, s[0:1]
	s_brev_b32 s0, -2
	v_bfi_b32 v4, s0, v8, v4
	v_mul_f32_e32 v5, 0.5, v5
	v_add_f32_e32 v4, 1.0, v4
	v_mul_f32_e32 v4, v5, v4
	v_cvt_pk_bf16_f32 v8, v4, s0
	v_lshl_add_u64 v[4:5], v[6:7], 1, s[44:45]
	global_store_short v[4:5], v8, off
	v_lshlrev_b64 v[4:5], 9, v[20:21]
	v_lshl_add_u64 v[4:5], v[4:5], 0, v[0:1]
	s_mov_b64 s[0:1], 0x4400
	v_lshl_add_u64 v[4:5], v[4:5], 0, s[0:1]
	v_lshl_add_u64 v[6:7], v[4:5], 1, s[36:37]
	v_mov_b32_e32 v6, v150
	v_lshlrev_b32_e32 v6, 16, v6
	v_fma_f32 v2, v28, v6, v2
	v_mul_f32_e32 v6, 0x3d372713, v2
	v_mul_f32_e32 v6, v2, v6
	v_fma_f32 v6, v2, v6, v2
	v_mul_f32_e32 v6, 0x3f4c422a, v6
	v_cmp_nlt_f32_e64 s[0:1], |v6|, s10
	s_and_saveexec_b64 s[2:3], s[0:1]
	s_xor_b64 s[0:1], exec, s[2:3]
	s_cbranch_execz .LBB0_1853
	v_add_f32_e64 v7, |v6|, |v6|
	v_mul_f32_e32 v8, 0x3fb8aa3b, v7
	v_rndne_f32_e32 v9, v8
	s_mov_b32 s2, 0x3fb8aa3b
	v_sub_f32_e32 v10, v8, v9
	v_fma_f32 v8, v7, s2, -v8
	v_fmac_f32_e32 v8, 0x32a5705f, v7
	v_add_f32_e32 v8, v10, v8
	v_cvt_i32_f32_e32 v9, v9
	v_exp_f32_e32 v8, v8
	s_mov_b32 s2, 0xc2ce8ed0
	v_cmp_ngt_f32_e32 vcc, s2, v7
	s_mov_b32 s2, 0x42b17218
	v_ldexp_f32 v8, v8, v9
	v_cndmask_b32_e32 v8, 0, v8, vcc
	v_cmp_nlt_f32_e32 vcc, s2, v7
	s_nop 1
	v_cndmask_b32_e32 v7, v235, v8, vcc
	v_add_f32_e32 v7, 1.0, v7
	v_rcp_f32_e32 v7, v7
	s_nop 0
	v_fma_f32 v7, v7, -2.0, 1.0
.LBB0_1853:
	s_andn2_saveexec_b64 s[0:1], s[0:1]
	v_mul_f32_e32 v7, v6, v6
	v_fmamk_f32 v8, v7, 0xbbbac73d, v204
	v_fmaak_f32 v8, v7, v8, 0xbd5c1c4e
	v_fmaak_f32 v8, v7, v8, 0x3e088382
	v_fmaak_f32 v8, v7, v8, 0xbeaaaa99
	v_mul_f32_e64 v8, |v6|, v8
	v_fma_f32 v7, v7, v8, |v6|
	s_or_b64 exec, exec, s[0:1]
	s_brev_b32 s0, -2
	v_bfi_b32 v6, s0, v7, v6
	v_mul_f32_e32 v2, 0.5, v2
	v_add_f32_e32 v6, 1.0, v6
	v_mul_f32_e32 v2, v2, v6
	v_cvt_pk_bf16_f32 v2, v2, s0
	v_lshl_add_u64 v[4:5], v[4:5], 1, s[44:45]
	global_store_short v[4:5], v2, off
	v_lshlrev_b64 v[4:5], 9, v[20:21]
	v_lshl_add_u64 v[4:5], v[4:5], 0, v[0:1]
	s_mov_b64 s[0:1], 0x4600
	v_lshl_add_u64 v[4:5], v[4:5], 0, s[0:1]
	v_lshl_add_u64 v[6:7], v[4:5], 1, s[36:37]
	v_mov_b32_e32 v2, v151
	v_lshlrev_b32_e32 v2, 16, v2
	v_fmac_f32_e32 v3, v28, v2
	v_mul_f32_e32 v2, 0x3d372713, v3
	v_mul_f32_e32 v2, v3, v2
	v_fma_f32 v2, v3, v2, v3
	v_mul_f32_e32 v2, 0x3f4c422a, v2
	v_cmp_nlt_f32_e64 s[0:1], |v2|, s10
	s_and_saveexec_b64 s[2:3], s[0:1]
	s_xor_b64 s[0:1], exec, s[2:3]
	s_cbranch_execz .LBB0_1857
	v_add_f32_e64 v6, |v2|, |v2|
	v_mul_f32_e32 v7, 0x3fb8aa3b, v6
	v_rndne_f32_e32 v8, v7
	s_mov_b32 s2, 0x3fb8aa3b
	v_sub_f32_e32 v9, v7, v8
	v_fma_f32 v7, v6, s2, -v7
	v_fmac_f32_e32 v7, 0x32a5705f, v6
	v_add_f32_e32 v7, v9, v7
	v_cvt_i32_f32_e32 v8, v8
	v_exp_f32_e32 v7, v7
	s_mov_b32 s2, 0xc2ce8ed0
	v_cmp_ngt_f32_e32 vcc, s2, v6
	s_mov_b32 s2, 0x42b17218
	v_ldexp_f32 v7, v7, v8
	v_cndmask_b32_e32 v7, 0, v7, vcc
	v_cmp_nlt_f32_e32 vcc, s2, v6
	s_nop 1
	v_cndmask_b32_e32 v6, v235, v7, vcc
	v_add_f32_e32 v6, 1.0, v6
	v_rcp_f32_e32 v6, v6
	s_nop 0
	v_fma_f32 v6, v6, -2.0, 1.0
.LBB0_1857:
	s_andn2_saveexec_b64 s[0:1], s[0:1]
	v_mul_f32_e32 v6, v2, v2
	v_fmamk_f32 v7, v6, 0xbbbac73d, v204
	v_fmaak_f32 v7, v6, v7, 0xbd5c1c4e
	v_fmaak_f32 v7, v6, v7, 0x3e088382
	v_fmaak_f32 v7, v6, v7, 0xbeaaaa99
	v_mul_f32_e64 v7, |v2|, v7
	v_fma_f32 v6, v6, v7, |v2|
	s_or_b64 exec, exec, s[0:1]
	s_brev_b32 s0, -2
	v_bfi_b32 v2, s0, v6, v2
	v_mul_f32_e32 v3, 0.5, v3
	v_add_f32_e32 v2, 1.0, v2
	v_mul_f32_e32 v2, v3, v2
	v_cvt_pk_bf16_f32 v6, v2, s0
	v_lshl_add_u64 v[2:3], v[4:5], 1, s[44:45]
	global_store_short v[2:3], v6, off
	v_lshlrev_b64 v[2:3], 9, v[20:21]
	v_lshl_add_u64 v[2:3], v[2:3], 0, v[0:1]
	s_mov_b64 s[0:1], 0x6000
	v_lshl_add_u64 v[2:3], v[2:3], 0, s[0:1]
	v_lshl_add_u64 v[4:5], v[2:3], 1, s[36:37]
	v_mov_b32_e32 v6, v152
	v_pk_add_f32 v[4:5], v[12:13], 0 op_sel_hi:[1,0]
	v_lshlrev_b32_e32 v6, 16, v6
	v_pk_add_f32 v[4:5], v[4:5], v[16:17]
	s_nop 0
	v_fma_f32 v4, v28, v6, v4
	v_mul_f32_e32 v6, 0x3d372713, v4
	v_mul_f32_e32 v6, v4, v6
	v_fma_f32 v6, v4, v6, v4
	v_mul_f32_e32 v6, 0x3f4c422a, v6
	v_cmp_nlt_f32_e64 s[0:1], |v6|, s10
	s_and_saveexec_b64 s[2:3], s[0:1]
	s_xor_b64 s[0:1], exec, s[2:3]
	s_cbranch_execz .LBB0_1861
	v_add_f32_e64 v7, |v6|, |v6|
	v_mul_f32_e32 v8, 0x3fb8aa3b, v7
	v_rndne_f32_e32 v9, v8
	s_mov_b32 s2, 0x3fb8aa3b
	v_sub_f32_e32 v10, v8, v9
	v_fma_f32 v8, v7, s2, -v8
	v_fmac_f32_e32 v8, 0x32a5705f, v7
	v_add_f32_e32 v8, v10, v8
	v_cvt_i32_f32_e32 v9, v9
	v_exp_f32_e32 v8, v8
	s_mov_b32 s2, 0xc2ce8ed0
	v_cmp_ngt_f32_e32 vcc, s2, v7
	s_mov_b32 s2, 0x42b17218
	v_ldexp_f32 v8, v8, v9
	v_cndmask_b32_e32 v8, 0, v8, vcc
	v_cmp_nlt_f32_e32 vcc, s2, v7
	s_nop 1
	v_cndmask_b32_e32 v7, v235, v8, vcc
	v_add_f32_e32 v7, 1.0, v7
	v_rcp_f32_e32 v7, v7
	s_nop 0
	v_fma_f32 v7, v7, -2.0, 1.0
.LBB0_1861:
	s_andn2_saveexec_b64 s[0:1], s[0:1]
	v_mul_f32_e32 v7, v6, v6
	v_fmamk_f32 v8, v7, 0xbbbac73d, v204
	v_fmaak_f32 v8, v7, v8, 0xbd5c1c4e
	v_fmaak_f32 v8, v7, v8, 0x3e088382
	v_fmaak_f32 v8, v7, v8, 0xbeaaaa99
	v_mul_f32_e64 v8, |v6|, v8
	v_fma_f32 v7, v7, v8, |v6|
	s_or_b64 exec, exec, s[0:1]
	s_brev_b32 s0, -2
	v_bfi_b32 v6, s0, v7, v6
	v_mul_f32_e32 v4, 0.5, v4
	v_add_f32_e32 v6, 1.0, v6
	v_mul_f32_e32 v4, v4, v6
	v_cvt_pk_bf16_f32 v4, v4, s0
	v_lshl_add_u64 v[2:3], v[2:3], 1, s[44:45]
	global_store_short v[2:3], v4, off
	v_lshlrev_b64 v[2:3], 9, v[20:21]
	v_lshl_add_u64 v[2:3], v[2:3], 0, v[0:1]
	s_mov_b64 s[0:1], 0x6200
	v_lshl_add_u64 v[6:7], v[2:3], 0, s[0:1]
	v_lshl_add_u64 v[2:3], v[6:7], 1, s[36:37]
	v_mov_b32_e32 v4, v153
	v_pk_add_f32 v[2:3], v[14:15], 0 op_sel_hi:[1,0]
	v_lshlrev_b32_e32 v4, 16, v4
	v_fmac_f32_e32 v5, v28, v4
	v_mul_f32_e32 v4, 0x3d372713, v5
	v_mul_f32_e32 v4, v5, v4
	v_fma_f32 v4, v5, v4, v5
	v_mul_f32_e32 v4, 0x3f4c422a, v4
	v_pk_add_f32 v[2:3], v[2:3], v[18:19]
	v_cmp_nlt_f32_e64 s[0:1], |v4|, s10
	s_and_saveexec_b64 s[2:3], s[0:1]
	s_xor_b64 s[0:1], exec, s[2:3]
	s_cbranch_execz .LBB0_1865
	v_add_f32_e64 v8, |v4|, |v4|
	v_mul_f32_e32 v9, 0x3fb8aa3b, v8
	v_rndne_f32_e32 v10, v9
	s_mov_b32 s2, 0x3fb8aa3b
	v_sub_f32_e32 v11, v9, v10
	v_fma_f32 v9, v8, s2, -v9
	v_fmac_f32_e32 v9, 0x32a5705f, v8
	v_add_f32_e32 v9, v11, v9
	v_cvt_i32_f32_e32 v10, v10
	v_exp_f32_e32 v9, v9
	s_mov_b32 s2, 0xc2ce8ed0
	v_cmp_ngt_f32_e32 vcc, s2, v8
	s_mov_b32 s2, 0x42b17218
	v_ldexp_f32 v9, v9, v10
	v_cndmask_b32_e32 v9, 0, v9, vcc
	v_cmp_nlt_f32_e32 vcc, s2, v8
	s_nop 1
	v_cndmask_b32_e32 v8, v235, v9, vcc
	v_add_f32_e32 v8, 1.0, v8
	v_rcp_f32_e32 v8, v8
	s_nop 0
	v_fma_f32 v8, v8, -2.0, 1.0
.LBB0_1865:
	s_andn2_saveexec_b64 s[0:1], s[0:1]
	v_mul_f32_e32 v8, v4, v4
	v_fmamk_f32 v9, v8, 0xbbbac73d, v204
	v_fmaak_f32 v9, v8, v9, 0xbd5c1c4e
	v_fmaak_f32 v9, v8, v9, 0x3e088382
	v_fmaak_f32 v9, v8, v9, 0xbeaaaa99
	v_mul_f32_e64 v9, |v4|, v9
	v_fma_f32 v8, v8, v9, |v4|
	s_or_b64 exec, exec, s[0:1]
	s_brev_b32 s0, -2
	v_bfi_b32 v4, s0, v8, v4
	v_mul_f32_e32 v5, 0.5, v5
	v_add_f32_e32 v4, 1.0, v4
	v_mul_f32_e32 v4, v5, v4
	v_cvt_pk_bf16_f32 v8, v4, s0
	v_lshl_add_u64 v[4:5], v[6:7], 1, s[44:45]
	global_store_short v[4:5], v8, off
	v_lshlrev_b64 v[4:5], 9, v[20:21]
	v_lshl_add_u64 v[4:5], v[4:5], 0, v[0:1]
	s_mov_b64 s[0:1], 0x6400
	v_lshl_add_u64 v[4:5], v[4:5], 0, s[0:1]
	v_lshl_add_u64 v[6:7], v[4:5], 1, s[36:37]
	v_mov_b32_e32 v6, v154
	v_lshlrev_b32_e32 v6, 16, v6
	v_fma_f32 v2, v28, v6, v2
	v_mul_f32_e32 v6, 0x3d372713, v2
	v_mul_f32_e32 v6, v2, v6
	v_fma_f32 v6, v2, v6, v2
	v_mul_f32_e32 v6, 0x3f4c422a, v6
	v_cmp_nlt_f32_e64 s[0:1], |v6|, s10
	s_and_saveexec_b64 s[2:3], s[0:1]
	s_xor_b64 s[0:1], exec, s[2:3]
	s_cbranch_execz .LBB0_1869
	v_add_f32_e64 v7, |v6|, |v6|
	v_mul_f32_e32 v8, 0x3fb8aa3b, v7
	v_rndne_f32_e32 v9, v8
	s_mov_b32 s2, 0x3fb8aa3b
	v_sub_f32_e32 v10, v8, v9
	v_fma_f32 v8, v7, s2, -v8
	v_fmac_f32_e32 v8, 0x32a5705f, v7
	v_add_f32_e32 v8, v10, v8
	v_cvt_i32_f32_e32 v9, v9
	v_exp_f32_e32 v8, v8
	s_mov_b32 s2, 0xc2ce8ed0
	v_cmp_ngt_f32_e32 vcc, s2, v7
	s_mov_b32 s2, 0x42b17218
	v_ldexp_f32 v8, v8, v9
	v_cndmask_b32_e32 v8, 0, v8, vcc
	v_cmp_nlt_f32_e32 vcc, s2, v7
	s_nop 1
	v_cndmask_b32_e32 v7, v235, v8, vcc
	v_add_f32_e32 v7, 1.0, v7
	v_rcp_f32_e32 v7, v7
	s_nop 0
	v_fma_f32 v7, v7, -2.0, 1.0
.LBB0_1869:
	s_andn2_saveexec_b64 s[0:1], s[0:1]
	v_mul_f32_e32 v7, v6, v6
	v_fmamk_f32 v8, v7, 0xbbbac73d, v204
	v_fmaak_f32 v8, v7, v8, 0xbd5c1c4e
	v_fmaak_f32 v8, v7, v8, 0x3e088382
	v_fmaak_f32 v8, v7, v8, 0xbeaaaa99
	v_mul_f32_e64 v8, |v6|, v8
	v_fma_f32 v7, v7, v8, |v6|
	s_or_b64 exec, exec, s[0:1]
	s_brev_b32 s0, -2
	v_bfi_b32 v6, s0, v7, v6
	v_mul_f32_e32 v2, 0.5, v2
	v_add_f32_e32 v6, 1.0, v6
	v_mul_f32_e32 v2, v2, v6
	v_cvt_pk_bf16_f32 v2, v2, s0
	v_lshl_add_u64 v[4:5], v[4:5], 1, s[44:45]
	global_store_short v[4:5], v2, off
	v_lshlrev_b64 v[4:5], 9, v[20:21]
	v_lshl_add_u64 v[0:1], v[4:5], 0, v[0:1]
	s_mov_b64 s[0:1], 0x6600
	v_lshl_add_u64 v[0:1], v[0:1], 0, s[0:1]
	v_lshl_add_u64 v[4:5], v[0:1], 1, s[36:37]
	v_mov_b32_e32 v2, v155
	v_lshlrev_b32_e32 v2, 16, v2
	v_fmac_f32_e32 v3, v28, v2
	v_mul_f32_e32 v2, 0x3d372713, v3
	v_mul_f32_e32 v2, v3, v2
	v_fma_f32 v2, v3, v2, v3
	v_mul_f32_e32 v2, 0x3f4c422a, v2
	v_cmp_nlt_f32_e64 s[0:1], |v2|, s10
	s_and_saveexec_b64 s[2:3], s[0:1]
	s_xor_b64 s[0:1], exec, s[2:3]
	s_cbranch_execz .LBB0_1873
	v_add_f32_e64 v4, |v2|, |v2|
	v_mul_f32_e32 v5, 0x3fb8aa3b, v4
	v_rndne_f32_e32 v6, v5
	s_mov_b32 s2, 0x3fb8aa3b
	v_sub_f32_e32 v7, v5, v6
	v_fma_f32 v5, v4, s2, -v5
	v_fmac_f32_e32 v5, 0x32a5705f, v4
	v_add_f32_e32 v5, v7, v5
	v_cvt_i32_f32_e32 v6, v6
	v_exp_f32_e32 v5, v5
	s_mov_b32 s2, 0xc2ce8ed0
	v_cmp_ngt_f32_e32 vcc, s2, v4
	s_mov_b32 s2, 0x42b17218
	v_ldexp_f32 v5, v5, v6
	v_cndmask_b32_e32 v5, 0, v5, vcc
	v_cmp_nlt_f32_e32 vcc, s2, v4
	s_nop 1
	v_cndmask_b32_e32 v4, v235, v5, vcc
	v_add_f32_e32 v4, 1.0, v4
	v_rcp_f32_e32 v4, v4
	s_nop 0
	v_fma_f32 v4, v4, -2.0, 1.0
